# adds: rowpass loops unrolled x3 with rotating register sets (two rows of loads in flight behind counted vmcnt)
# baseline (speedup 1.0000x reference)
.LBB0_93:
	v_mov_b32_e32 v0, v204
	s_nop 0
	v_ashrrev_i32_e32 v0, 6, v0
	v_add_u32_e32 v16, s69, v0
	v_mov_b32_e32 v0, v204
	v_cmp_gt_i32_e32 vcc, s28, v16
	s_and_saveexec_b64 s[2:3], vcc
	s_cbranch_execz .LBB0_96
	v_readlane_b32 s4, v255, 21
	v_readlane_b32 s5, v255, 22
	s_lshl_b32 s4, s4, 10
	s_ashr_i32 s5, s4, 31
	v_readlane_b32 s8, v252, 0
	s_lshl_b64 s[4:5], s[4:5], 2
	v_readlane_b32 s10, v252, 2
	v_readlane_b32 s11, v252, 3
	v_readlane_b32 s9, v252, 1
	s_add_u32 s4, s8, s4
	v_ashrrev_i32_e32 v17, 31, v16
	v_readlane_b32 s10, v253, 2
	v_lshlrev_b32_e32 v0, 2, v0
	s_addc_u32 s5, s9, s5
	v_lshlrev_b64 v[2:3], 11, v[16:17]
	v_readlane_b32 s11, v253, 3
	v_and_b32_e32 v6, 0xfc, v0
	v_readlane_b32 s8, v253, 0
	v_add_u32_e32 v17, s70, v16
	v_lshl_add_u64 v[4:5], s[10:11], 0, v[2:3]
	v_lshlrev_b32_e32 v188, 1, v6
	v_readlane_b32 s9, v253, 1
	v_cmp_gt_i32_e32 vcc, s28, v17
	v_lshl_add_u64 v[0:1], v[4:5], 0, v[188:189]
	v_lshl_add_u64 v[2:3], s[8:9], 0, v[2:3]
	v_cndmask_b32_e32 v18, v16, v17, vcc
	v_lshl_add_u64 v[2:3], v[2:3], 0, v[188:189]
	global_load_dwordx2 v[52:53], v[0:1], off
	global_load_dwordx2 v[48:49], v[0:1], off offset:512
	global_load_dwordx2 v[44:45], v[0:1], off offset:1024
	global_load_dwordx2 v[40:41], v[0:1], off offset:1536
	global_load_dwordx2 v[54:55], v[2:3], off
	global_load_dwordx2 v[50:51], v[2:3], off offset:512
	global_load_dwordx2 v[46:47], v[2:3], off offset:1024
	global_load_dwordx2 v[42:43], v[2:3], off offset:1536
	v_ashrrev_i32_e32 v19, 31, v18
	v_lshlrev_b64 v[22:23], 11, v[18:19]
	v_lshl_add_u64 v[18:19], s[8:9], 0, v[22:23]
	v_lshl_add_u64 v[22:23], s[10:11], 0, v[22:23]
	v_lshlrev_b32_e32 v12, 2, v6
	v_lshl_add_u64 v[26:27], v[18:19], 0, v[188:189]
	v_lshl_add_u64 v[22:23], v[22:23], 0, v[188:189]
	global_load_dwordx4 v[0:3], v12, s[4:5]
	global_load_dwordx4 v[4:7], v12, s[4:5] offset:1024
	global_load_dwordx4 v[8:11], v12, s[4:5] offset:2048
	s_nop 0
	global_load_dwordx4 v[12:15], v12, s[4:5] offset:3072
	s_nop 0
	global_load_dwordx2 v[18:19], v[26:27], off offset:1536
	global_load_dwordx2 v[20:21], v[26:27], off offset:1024
	global_load_dwordx2 v[24:25], v[26:27], off offset:512
	s_nop 0
	global_load_dwordx2 v[26:27], v[26:27], off
	s_nop 0
	global_load_dwordx2 v[30:31], v[22:23], off offset:1536
	global_load_dwordx2 v[34:35], v[22:23], off offset:1024
	global_load_dwordx2 v[36:37], v[22:23], off offset:512
	global_load_dwordx2 v[38:39], v[22:23], off
	v_readlane_b32 s4, v254, 32
	v_readlane_b32 s5, v254, 33
	v_lshl_add_u64 v[22:23], s[10:11], 0, v[188:189]
	v_lshl_add_u64 v[28:29], s[8:9], 0, v[188:189]
	v_lshl_add_u64 v[32:33], s[4:5], 0, v[188:189]
	s_mov_b64 s[4:5], 0
	v_readlane_b32 s12, v252, 4
	v_readlane_b32 s13, v252, 5
	v_readlane_b32 s14, v252, 6
	v_readlane_b32 s15, v252, 7
	s_waitcnt vmcnt(0)
.LBB0_95:
	v_add_u32_e32 v104, s71, v16
	v_cmp_gt_i32_e32 vcc, s28, v104
	s_nop 1
	v_cndmask_b32_e32 v56, v16, v104, vcc
	v_ashrrev_i32_e32 v57, 31, v56
	v_lshlrev_b64 v[56:57], 11, v[56:57]
	v_lshl_add_u64 v[62:63], v[22:23], 0, v[56:57]
	v_lshl_add_u64 v[70:71], v[28:29], 0, v[56:57]
	global_load_dwordx2 v[56:57], v[62:63], off
	global_load_dwordx2 v[58:59], v[62:63], off offset:512
	global_load_dwordx2 v[60:61], v[62:63], off offset:1024
	s_nop 0
	global_load_dwordx2 v[62:63], v[62:63], off offset:1536
	s_nop 0
	global_load_dwordx2 v[64:65], v[70:71], off
	global_load_dwordx2 v[66:67], v[70:71], off offset:512
	global_load_dwordx2 v[68:69], v[70:71], off offset:1024
	s_nop 0
	global_load_dwordx2 v[70:71], v[70:71], off offset:1536
	v_and_b32_e32 v17, 64, v207
	v_add_u32_e32 v17, 64, v17
	v_xor_b32_e32 v72, 32, v207
	v_cmp_lt_i32_e32 vcc, v72, v17
	s_waitcnt vmcnt(24)
	v_and_b32_e32 v73, 0xffff0000, v53
	v_lshlrev_b32_e32 v78, 16, v52
	v_cndmask_b32_e32 v72, v207, v72, vcc
	v_lshlrev_b32_e32 v105, 2, v72
	v_xor_b32_e32 v72, 16, v207
	v_cmp_lt_i32_e32 vcc, v72, v17
	v_and_b32_e32 v79, 0xffff0000, v52
	v_lshlrev_b32_e32 v52, 16, v54
	v_cndmask_b32_e32 v72, v207, v72, vcc
	v_lshlrev_b32_e32 v106, 2, v72
	v_xor_b32_e32 v72, 8, v207
	v_cmp_lt_i32_e32 vcc, v72, v17
	v_lshlrev_b32_e32 v74, 16, v55
	v_and_b32_e32 v75, 0xffff0000, v55
	v_cndmask_b32_e32 v72, v207, v72, vcc
	v_lshlrev_b32_e32 v107, 2, v72
	v_xor_b32_e32 v72, 4, v207
	v_cmp_lt_i32_e32 vcc, v72, v17
	v_pk_mul_f32 v[76:77], v[74:75], v[74:75]
	v_lshlrev_b32_e32 v80, 16, v49
	v_cndmask_b32_e32 v72, v207, v72, vcc
	v_lshlrev_b32_e32 v108, 2, v72
	v_xor_b32_e32 v72, 2, v207
	v_cmp_lt_i32_e32 vcc, v72, v17
	s_waitcnt lgkmcnt(0)
	v_and_b32_e32 v81, 0xffff0000, v49
	v_lshlrev_b32_e32 v86, 16, v48
	v_cndmask_b32_e32 v72, v207, v72, vcc
	v_lshlrev_b32_e32 v109, 2, v72
	v_xor_b32_e32 v72, 1, v207
	v_cmp_lt_i32_e32 vcc, v72, v17
	v_and_b32_e32 v87, 0xffff0000, v48
	v_lshlrev_b32_e32 v48, 16, v50
	v_cndmask_b32_e32 v17, v207, v72, vcc
	v_lshlrev_b32_e32 v72, 16, v53
	v_and_b32_e32 v53, 0xffff0000, v54
	v_pk_mul_f32 v[54:55], v[52:53], v[52:53]
	v_and_b32_e32 v49, 0xffff0000, v50
	v_add_f32_e32 v54, v54, v55
	v_add_f32_e32 v54, v76, v54
	v_lshlrev_b32_e32 v82, 16, v51
	v_and_b32_e32 v83, 0xffff0000, v51
	v_pk_mul_f32 v[50:51], v[48:49], v[48:49]
	v_add_f32_e32 v54, v77, v54
	v_add_f32_e32 v50, v50, v54
	v_pk_mul_f32 v[84:85], v[82:83], v[82:83]
	v_add_f32_e32 v50, v51, v50
	v_lshlrev_b32_e32 v88, 16, v45
	v_and_b32_e32 v89, 0xffff0000, v45
	v_lshlrev_b32_e32 v94, 16, v44
	v_and_b32_e32 v95, 0xffff0000, v44
	v_lshlrev_b32_e32 v44, 16, v46
	v_and_b32_e32 v45, 0xffff0000, v46
	v_add_f32_e32 v50, v84, v50
	v_lshlrev_b32_e32 v90, 16, v47
	v_and_b32_e32 v91, 0xffff0000, v47
	v_pk_mul_f32 v[46:47], v[44:45], v[44:45]
	v_add_f32_e32 v50, v85, v50
	v_add_f32_e32 v46, v46, v50
	v_pk_mul_f32 v[92:93], v[90:91], v[90:91]
	v_add_f32_e32 v46, v47, v46
	v_lshlrev_b32_e32 v96, 16, v41
	v_and_b32_e32 v97, 0xffff0000, v41
	v_lshlrev_b32_e32 v102, 16, v40
	v_and_b32_e32 v103, 0xffff0000, v40
	v_lshlrev_b32_e32 v40, 16, v42
	v_and_b32_e32 v41, 0xffff0000, v42
	v_add_f32_e32 v46, v92, v46
	v_lshlrev_b32_e32 v98, 16, v43
	v_and_b32_e32 v99, 0xffff0000, v43
	v_pk_mul_f32 v[42:43], v[40:41], v[40:41]
	v_add_f32_e32 v46, v93, v46
	v_add_f32_e32 v42, v42, v46
	v_pk_mul_f32 v[100:101], v[98:99], v[98:99]
	v_add_f32_e32 v42, v43, v42
	v_add_f32_e32 v42, v100, v42
	v_add_f32_e32 v42, v101, v42
	ds_bpermute_b32 v43, v105, v42
	v_lshlrev_b32_e32 v17, 2, v17
	s_waitcnt lgkmcnt(0)
	v_add_f32_e32 v42, v42, v43
	ds_bpermute_b32 v43, v106, v42
	s_waitcnt lgkmcnt(0)
	v_add_f32_e32 v42, v42, v43
	ds_bpermute_b32 v43, v107, v42
	s_waitcnt lgkmcnt(0)
	v_add_f32_e32 v42, v42, v43
	ds_bpermute_b32 v43, v108, v42
	s_waitcnt lgkmcnt(0)
	v_add_f32_e32 v42, v42, v43
	ds_bpermute_b32 v43, v109, v42
	s_waitcnt lgkmcnt(0)
	v_add_f32_e32 v42, v42, v43
	ds_bpermute_b32 v17, v17, v42
	s_waitcnt lgkmcnt(0)
	v_add_f32_e32 v17, v42, v17
	v_fmamk_f32 v17, v17, 0x3a800000, v205
	v_cmp_gt_f32_e32 vcc, s30, v17
	v_mul_f32_e32 v42, 0x4b800000, v17
	s_nop 0
	v_cndmask_b32_e32 v17, v17, v42, vcc
	v_rsq_f32_e32 v17, v17
	s_nop 0
	v_mul_f32_e32 v42, 0x45800000, v17
	v_cndmask_b32_e32 v42, v17, v42, vcc
	v_pk_mul_f32 v[46:47], v[42:43], v[52:53] op_sel_hi:[0,1]
	v_pk_mul_f32 v[50:51], v[42:43], v[74:75] op_sel_hi:[0,1]
	v_ashrrev_i32_e32 v17, 31, v16
	v_pk_fma_f32 v[46:47], v[0:1], v[46:47], v[78:79]
	v_pk_fma_f32 v[50:51], v[2:3], v[50:51], v[72:73]
	v_pk_mul_f32 v[48:49], v[42:43], v[48:49] op_sel_hi:[0,1]
	v_pk_mul_f32 v[52:53], v[42:43], v[82:83] op_sel_hi:[0,1]
	v_pk_mul_f32 v[44:45], v[42:43], v[44:45] op_sel_hi:[0,1]
	v_pk_mul_f32 v[54:55], v[42:43], v[90:91] op_sel_hi:[0,1]
	v_pk_mul_f32 v[40:41], v[42:43], v[40:41] op_sel_hi:[0,1]
	v_pk_mul_f32 v[42:43], v[42:43], v[98:99] op_sel_hi:[0,1]
	v_lshlrev_b64 v[16:17], 11, v[16:17]
	v_pk_fma_f32 v[48:49], v[4:5], v[48:49], v[86:87]
	v_pk_fma_f32 v[52:53], v[6:7], v[52:53], v[80:81]
	v_pk_fma_f32 v[44:45], v[8:9], v[44:45], v[94:95]
	v_pk_fma_f32 v[54:55], v[10:11], v[54:55], v[88:89]
	v_pk_fma_f32 v[40:41], v[12:13], v[40:41], v[102:103]
	v_pk_fma_f32 v[42:43], v[14:15], v[42:43], v[96:97]
	v_lshl_add_u64 v[16:17], v[32:33], 0, v[16:17]
	v_cvt_pk_bf16_f32 v46, v46, v47
	v_cvt_pk_bf16_f32 v47, v50, v51
	global_store_dwordx2 v[16:17], v[46:47], off
	v_cvt_pk_bf16_f32 v46, v48, v49
	v_cvt_pk_bf16_f32 v47, v52, v53
	v_cvt_pk_bf16_f32 v44, v44, v45
	v_cvt_pk_bf16_f32 v45, v54, v55
	v_cvt_pk_bf16_f32 v40, v40, v41
	v_cvt_pk_bf16_f32 v41, v42, v43
	global_store_dwordx2 v[16:17], v[46:47], off offset:512
	global_store_dwordx2 v[16:17], v[44:45], off offset:1024
	global_store_dwordx2 v[16:17], v[40:41], off offset:1536
	v_subrev_u32_e32 v16, s70, v104
	v_cmp_lt_i32_e32 vcc, s31, v16
	s_or_b64 s[4:5], vcc, s[4:5]
	s_andn2_b64 exec, exec, s[4:5]
	s_cbranch_execz .LBB0_96
.Lrp95_top1:
	v_add_u32_e32 v104, s71, v16
	v_cmp_gt_i32_e32 vcc, s28, v104
	s_nop 1
	v_cndmask_b32_e32 v52, v16, v104, vcc
	v_ashrrev_i32_e32 v53, 31, v52
	v_lshlrev_b64 v[52:53], 11, v[52:53]
	v_lshl_add_u64 v[40:41], v[22:23], 0, v[52:53]
	v_lshl_add_u64 v[42:43], v[28:29], 0, v[52:53]
	global_load_dwordx2 v[52:53], v[40:41], off
	global_load_dwordx2 v[48:49], v[40:41], off offset:512
	global_load_dwordx2 v[44:45], v[40:41], off offset:1024
	s_nop 0
	global_load_dwordx2 v[40:41], v[40:41], off offset:1536
	s_nop 0
	global_load_dwordx2 v[54:55], v[42:43], off
	global_load_dwordx2 v[50:51], v[42:43], off offset:512
	global_load_dwordx2 v[46:47], v[42:43], off offset:1024
	s_nop 0
	global_load_dwordx2 v[42:43], v[42:43], off offset:1536
	v_and_b32_e32 v17, 64, v207
	v_add_u32_e32 v17, 64, v17
	v_xor_b32_e32 v72, 32, v207
	v_cmp_lt_i32_e32 vcc, v72, v17
	s_waitcnt vmcnt(24)
	v_and_b32_e32 v73, 0xffff0000, v39
	v_lshlrev_b32_e32 v78, 16, v38
	v_cndmask_b32_e32 v72, v207, v72, vcc
	v_lshlrev_b32_e32 v105, 2, v72
	v_xor_b32_e32 v72, 16, v207
	v_cmp_lt_i32_e32 vcc, v72, v17
	v_and_b32_e32 v79, 0xffff0000, v38
	v_lshlrev_b32_e32 v38, 16, v26
	v_cndmask_b32_e32 v72, v207, v72, vcc
	v_lshlrev_b32_e32 v106, 2, v72
	v_xor_b32_e32 v72, 8, v207
	v_cmp_lt_i32_e32 vcc, v72, v17
	v_lshlrev_b32_e32 v74, 16, v27
	v_and_b32_e32 v75, 0xffff0000, v27
	v_cndmask_b32_e32 v72, v207, v72, vcc
	v_lshlrev_b32_e32 v107, 2, v72
	v_xor_b32_e32 v72, 4, v207
	v_cmp_lt_i32_e32 vcc, v72, v17
	v_pk_mul_f32 v[76:77], v[74:75], v[74:75]
	v_lshlrev_b32_e32 v80, 16, v37
	v_cndmask_b32_e32 v72, v207, v72, vcc
	v_lshlrev_b32_e32 v108, 2, v72
	v_xor_b32_e32 v72, 2, v207
	v_cmp_lt_i32_e32 vcc, v72, v17
	s_waitcnt lgkmcnt(0)
	v_and_b32_e32 v81, 0xffff0000, v37
	v_lshlrev_b32_e32 v86, 16, v36
	v_cndmask_b32_e32 v72, v207, v72, vcc
	v_lshlrev_b32_e32 v109, 2, v72
	v_xor_b32_e32 v72, 1, v207
	v_cmp_lt_i32_e32 vcc, v72, v17
	v_and_b32_e32 v87, 0xffff0000, v36
	v_lshlrev_b32_e32 v36, 16, v24
	v_cndmask_b32_e32 v17, v207, v72, vcc
	v_lshlrev_b32_e32 v72, 16, v39
	v_and_b32_e32 v39, 0xffff0000, v26
	v_pk_mul_f32 v[26:27], v[38:39], v[38:39]
	v_and_b32_e32 v37, 0xffff0000, v24
	v_add_f32_e32 v26, v26, v27
	v_add_f32_e32 v26, v76, v26
	v_lshlrev_b32_e32 v82, 16, v25
	v_and_b32_e32 v83, 0xffff0000, v25
	v_pk_mul_f32 v[24:25], v[36:37], v[36:37]
	v_add_f32_e32 v26, v77, v26
	v_add_f32_e32 v24, v24, v26
	v_pk_mul_f32 v[84:85], v[82:83], v[82:83]
	v_add_f32_e32 v24, v25, v24
	v_lshlrev_b32_e32 v88, 16, v35
	v_and_b32_e32 v89, 0xffff0000, v35
	v_lshlrev_b32_e32 v94, 16, v34
	v_and_b32_e32 v95, 0xffff0000, v34
	v_lshlrev_b32_e32 v34, 16, v20
	v_and_b32_e32 v35, 0xffff0000, v20
	v_add_f32_e32 v24, v84, v24
	v_lshlrev_b32_e32 v90, 16, v21
	v_and_b32_e32 v91, 0xffff0000, v21
	v_pk_mul_f32 v[20:21], v[34:35], v[34:35]
	v_add_f32_e32 v24, v85, v24
	v_add_f32_e32 v20, v20, v24
	v_pk_mul_f32 v[92:93], v[90:91], v[90:91]
	v_add_f32_e32 v20, v21, v20
	v_lshlrev_b32_e32 v96, 16, v31
	v_and_b32_e32 v97, 0xffff0000, v31
	v_lshlrev_b32_e32 v102, 16, v30
	v_and_b32_e32 v103, 0xffff0000, v30
	v_lshlrev_b32_e32 v30, 16, v18
	v_and_b32_e32 v31, 0xffff0000, v18
	v_add_f32_e32 v20, v92, v20
	v_lshlrev_b32_e32 v98, 16, v19
	v_and_b32_e32 v99, 0xffff0000, v19
	v_pk_mul_f32 v[18:19], v[30:31], v[30:31]
	v_add_f32_e32 v20, v93, v20
	v_add_f32_e32 v18, v18, v20
	v_pk_mul_f32 v[100:101], v[98:99], v[98:99]
	v_add_f32_e32 v18, v19, v18
	v_add_f32_e32 v18, v100, v18
	v_add_f32_e32 v18, v101, v18
	ds_bpermute_b32 v19, v105, v18
	v_lshlrev_b32_e32 v17, 2, v17
	s_waitcnt lgkmcnt(0)
	v_add_f32_e32 v18, v18, v19
	ds_bpermute_b32 v19, v106, v18
	s_waitcnt lgkmcnt(0)
	v_add_f32_e32 v18, v18, v19
	ds_bpermute_b32 v19, v107, v18
	s_waitcnt lgkmcnt(0)
	v_add_f32_e32 v18, v18, v19
	ds_bpermute_b32 v19, v108, v18
	s_waitcnt lgkmcnt(0)
	v_add_f32_e32 v18, v18, v19
	ds_bpermute_b32 v19, v109, v18
	s_waitcnt lgkmcnt(0)
	v_add_f32_e32 v18, v18, v19
	ds_bpermute_b32 v17, v17, v18
	s_waitcnt lgkmcnt(0)
	v_add_f32_e32 v17, v18, v17
	v_fmamk_f32 v17, v17, 0x3a800000, v205
	v_cmp_gt_f32_e32 vcc, s30, v17
	v_mul_f32_e32 v18, 0x4b800000, v17
	s_nop 0
	v_cndmask_b32_e32 v17, v17, v18, vcc
	v_rsq_f32_e32 v17, v17
	s_nop 0
	v_mul_f32_e32 v18, 0x45800000, v17
	v_cndmask_b32_e32 v18, v17, v18, vcc
	v_pk_mul_f32 v[20:21], v[18:19], v[38:39] op_sel_hi:[0,1]
	v_pk_mul_f32 v[24:25], v[18:19], v[74:75] op_sel_hi:[0,1]
	v_ashrrev_i32_e32 v17, 31, v16
	v_pk_fma_f32 v[20:21], v[0:1], v[20:21], v[78:79]
	v_pk_fma_f32 v[24:25], v[2:3], v[24:25], v[72:73]
	v_pk_mul_f32 v[36:37], v[18:19], v[36:37] op_sel_hi:[0,1]
	v_pk_mul_f32 v[38:39], v[18:19], v[82:83] op_sel_hi:[0,1]
	v_pk_mul_f32 v[34:35], v[18:19], v[34:35] op_sel_hi:[0,1]
	v_pk_mul_f32 v[26:27], v[18:19], v[90:91] op_sel_hi:[0,1]
	v_pk_mul_f32 v[30:31], v[18:19], v[30:31] op_sel_hi:[0,1]
	v_pk_mul_f32 v[18:19], v[18:19], v[98:99] op_sel_hi:[0,1]
	v_lshlrev_b64 v[16:17], 11, v[16:17]
	v_pk_fma_f32 v[36:37], v[4:5], v[36:37], v[86:87]
	v_pk_fma_f32 v[38:39], v[6:7], v[38:39], v[80:81]
	v_pk_fma_f32 v[34:35], v[8:9], v[34:35], v[94:95]
	v_pk_fma_f32 v[26:27], v[10:11], v[26:27], v[88:89]
	v_pk_fma_f32 v[30:31], v[12:13], v[30:31], v[102:103]
	v_pk_fma_f32 v[18:19], v[14:15], v[18:19], v[96:97]
	v_lshl_add_u64 v[16:17], v[32:33], 0, v[16:17]
	v_cvt_pk_bf16_f32 v20, v20, v21
	v_cvt_pk_bf16_f32 v21, v24, v25
	global_store_dwordx2 v[16:17], v[20:21], off
	v_cvt_pk_bf16_f32 v20, v36, v37
	v_cvt_pk_bf16_f32 v21, v38, v39
	v_cvt_pk_bf16_f32 v34, v34, v35
	v_cvt_pk_bf16_f32 v35, v26, v27
	v_cvt_pk_bf16_f32 v30, v30, v31
	v_cvt_pk_bf16_f32 v31, v18, v19
	global_store_dwordx2 v[16:17], v[20:21], off offset:512
	global_store_dwordx2 v[16:17], v[34:35], off offset:1024
	global_store_dwordx2 v[16:17], v[30:31], off offset:1536
	v_subrev_u32_e32 v16, s70, v104
	v_cmp_lt_i32_e32 vcc, s31, v16
	s_or_b64 s[4:5], vcc, s[4:5]
	s_andn2_b64 exec, exec, s[4:5]
	s_cbranch_execz .LBB0_96
.Lrp95_top2:
	v_add_u32_e32 v104, s71, v16
	v_cmp_gt_i32_e32 vcc, s28, v104
	s_nop 1
	v_cndmask_b32_e32 v38, v16, v104, vcc
	v_ashrrev_i32_e32 v39, 31, v38
	v_lshlrev_b64 v[38:39], 11, v[38:39]
	v_lshl_add_u64 v[30:31], v[22:23], 0, v[38:39]
	v_lshl_add_u64 v[18:19], v[28:29], 0, v[38:39]
	global_load_dwordx2 v[38:39], v[30:31], off
	global_load_dwordx2 v[36:37], v[30:31], off offset:512
	global_load_dwordx2 v[34:35], v[30:31], off offset:1024
	s_nop 0
	global_load_dwordx2 v[30:31], v[30:31], off offset:1536
	s_nop 0
	global_load_dwordx2 v[26:27], v[18:19], off
	global_load_dwordx2 v[24:25], v[18:19], off offset:512
	global_load_dwordx2 v[20:21], v[18:19], off offset:1024
	s_nop 0
	global_load_dwordx2 v[18:19], v[18:19], off offset:1536
	v_and_b32_e32 v17, 64, v207
	v_add_u32_e32 v17, 64, v17
	v_xor_b32_e32 v72, 32, v207
	v_cmp_lt_i32_e32 vcc, v72, v17
	s_waitcnt vmcnt(24)
	v_and_b32_e32 v73, 0xffff0000, v57
	v_lshlrev_b32_e32 v78, 16, v56
	v_cndmask_b32_e32 v72, v207, v72, vcc
	v_lshlrev_b32_e32 v105, 2, v72
	v_xor_b32_e32 v72, 16, v207
	v_cmp_lt_i32_e32 vcc, v72, v17
	v_and_b32_e32 v79, 0xffff0000, v56
	v_lshlrev_b32_e32 v56, 16, v64
	v_cndmask_b32_e32 v72, v207, v72, vcc
	v_lshlrev_b32_e32 v106, 2, v72
	v_xor_b32_e32 v72, 8, v207
	v_cmp_lt_i32_e32 vcc, v72, v17
	v_lshlrev_b32_e32 v74, 16, v65
	v_and_b32_e32 v75, 0xffff0000, v65
	v_cndmask_b32_e32 v72, v207, v72, vcc
	v_lshlrev_b32_e32 v107, 2, v72
	v_xor_b32_e32 v72, 4, v207
	v_cmp_lt_i32_e32 vcc, v72, v17
	v_pk_mul_f32 v[76:77], v[74:75], v[74:75]
	v_lshlrev_b32_e32 v80, 16, v59
	v_cndmask_b32_e32 v72, v207, v72, vcc
	v_lshlrev_b32_e32 v108, 2, v72
	v_xor_b32_e32 v72, 2, v207
	v_cmp_lt_i32_e32 vcc, v72, v17
	s_waitcnt lgkmcnt(0)
	v_and_b32_e32 v81, 0xffff0000, v59
	v_lshlrev_b32_e32 v86, 16, v58
	v_cndmask_b32_e32 v72, v207, v72, vcc
	v_lshlrev_b32_e32 v109, 2, v72
	v_xor_b32_e32 v72, 1, v207
	v_cmp_lt_i32_e32 vcc, v72, v17
	v_and_b32_e32 v87, 0xffff0000, v58
	v_lshlrev_b32_e32 v58, 16, v66
	v_cndmask_b32_e32 v17, v207, v72, vcc
	v_lshlrev_b32_e32 v72, 16, v57
	v_and_b32_e32 v57, 0xffff0000, v64
	v_pk_mul_f32 v[64:65], v[56:57], v[56:57]
	v_and_b32_e32 v59, 0xffff0000, v66
	v_add_f32_e32 v64, v64, v65
	v_add_f32_e32 v64, v76, v64
	v_lshlrev_b32_e32 v82, 16, v67
	v_and_b32_e32 v83, 0xffff0000, v67
	v_pk_mul_f32 v[66:67], v[58:59], v[58:59]
	v_add_f32_e32 v64, v77, v64
	v_add_f32_e32 v66, v66, v64
	v_pk_mul_f32 v[84:85], v[82:83], v[82:83]
	v_add_f32_e32 v66, v67, v66
	v_lshlrev_b32_e32 v88, 16, v61
	v_and_b32_e32 v89, 0xffff0000, v61
	v_lshlrev_b32_e32 v94, 16, v60
	v_and_b32_e32 v95, 0xffff0000, v60
	v_lshlrev_b32_e32 v60, 16, v68
	v_and_b32_e32 v61, 0xffff0000, v68
	v_add_f32_e32 v66, v84, v66
	v_lshlrev_b32_e32 v90, 16, v69
	v_and_b32_e32 v91, 0xffff0000, v69
	v_pk_mul_f32 v[68:69], v[60:61], v[60:61]
	v_add_f32_e32 v66, v85, v66
	v_add_f32_e32 v68, v68, v66
	v_pk_mul_f32 v[92:93], v[90:91], v[90:91]
	v_add_f32_e32 v68, v69, v68
	v_lshlrev_b32_e32 v96, 16, v63
	v_and_b32_e32 v97, 0xffff0000, v63
	v_lshlrev_b32_e32 v102, 16, v62
	v_and_b32_e32 v103, 0xffff0000, v62
	v_lshlrev_b32_e32 v62, 16, v70
	v_and_b32_e32 v63, 0xffff0000, v70
	v_add_f32_e32 v68, v92, v68
	v_lshlrev_b32_e32 v98, 16, v71
	v_and_b32_e32 v99, 0xffff0000, v71
	v_pk_mul_f32 v[70:71], v[62:63], v[62:63]
	v_add_f32_e32 v68, v93, v68
	v_add_f32_e32 v70, v70, v68
	v_pk_mul_f32 v[100:101], v[98:99], v[98:99]
	v_add_f32_e32 v70, v71, v70
	v_add_f32_e32 v70, v100, v70
	v_add_f32_e32 v70, v101, v70
	ds_bpermute_b32 v71, v105, v70
	v_lshlrev_b32_e32 v17, 2, v17
	s_waitcnt lgkmcnt(0)
	v_add_f32_e32 v70, v70, v71
	ds_bpermute_b32 v71, v106, v70
	s_waitcnt lgkmcnt(0)
	v_add_f32_e32 v70, v70, v71
	ds_bpermute_b32 v71, v107, v70
	s_waitcnt lgkmcnt(0)
	v_add_f32_e32 v70, v70, v71
	ds_bpermute_b32 v71, v108, v70
	s_waitcnt lgkmcnt(0)
	v_add_f32_e32 v70, v70, v71
	ds_bpermute_b32 v71, v109, v70
	s_waitcnt lgkmcnt(0)
	v_add_f32_e32 v70, v70, v71
	ds_bpermute_b32 v17, v17, v70
	s_waitcnt lgkmcnt(0)
	v_add_f32_e32 v17, v70, v17
	v_fmamk_f32 v17, v17, 0x3a800000, v205
	v_cmp_gt_f32_e32 vcc, s30, v17
	v_mul_f32_e32 v70, 0x4b800000, v17
	s_nop 0
	v_cndmask_b32_e32 v17, v17, v70, vcc
	v_rsq_f32_e32 v17, v17
	s_nop 0
	v_mul_f32_e32 v70, 0x45800000, v17
	v_cndmask_b32_e32 v70, v17, v70, vcc
	v_pk_mul_f32 v[68:69], v[70:71], v[56:57] op_sel_hi:[0,1]
	v_pk_mul_f32 v[66:67], v[70:71], v[74:75] op_sel_hi:[0,1]
	v_ashrrev_i32_e32 v17, 31, v16
	v_pk_fma_f32 v[68:69], v[0:1], v[68:69], v[78:79]
	v_pk_fma_f32 v[66:67], v[2:3], v[66:67], v[72:73]
	v_pk_mul_f32 v[58:59], v[70:71], v[58:59] op_sel_hi:[0,1]
	v_pk_mul_f32 v[56:57], v[70:71], v[82:83] op_sel_hi:[0,1]
	v_pk_mul_f32 v[60:61], v[70:71], v[60:61] op_sel_hi:[0,1]
	v_pk_mul_f32 v[64:65], v[70:71], v[90:91] op_sel_hi:[0,1]
	v_pk_mul_f32 v[62:63], v[70:71], v[62:63] op_sel_hi:[0,1]
	v_pk_mul_f32 v[70:71], v[70:71], v[98:99] op_sel_hi:[0,1]
	v_lshlrev_b64 v[16:17], 11, v[16:17]
	v_pk_fma_f32 v[58:59], v[4:5], v[58:59], v[86:87]
	v_pk_fma_f32 v[56:57], v[6:7], v[56:57], v[80:81]
	v_pk_fma_f32 v[60:61], v[8:9], v[60:61], v[94:95]
	v_pk_fma_f32 v[64:65], v[10:11], v[64:65], v[88:89]
	v_pk_fma_f32 v[62:63], v[12:13], v[62:63], v[102:103]
	v_pk_fma_f32 v[70:71], v[14:15], v[70:71], v[96:97]
	v_lshl_add_u64 v[16:17], v[32:33], 0, v[16:17]
	v_cvt_pk_bf16_f32 v68, v68, v69
	v_cvt_pk_bf16_f32 v69, v66, v67
	global_store_dwordx2 v[16:17], v[68:69], off
	v_cvt_pk_bf16_f32 v68, v58, v59
	v_cvt_pk_bf16_f32 v69, v56, v57
	v_cvt_pk_bf16_f32 v60, v60, v61
	v_cvt_pk_bf16_f32 v61, v64, v65
	v_cvt_pk_bf16_f32 v62, v62, v63
	v_cvt_pk_bf16_f32 v63, v70, v71
	global_store_dwordx2 v[16:17], v[68:69], off offset:512
	global_store_dwordx2 v[16:17], v[60:61], off offset:1024
	global_store_dwordx2 v[16:17], v[62:63], off offset:1536
	v_subrev_u32_e32 v16, s70, v104
	v_cmp_lt_i32_e32 vcc, s31, v16
	s_or_b64 s[4:5], vcc, s[4:5]
	s_andn2_b64 exec, exec, s[4:5]
	s_cbranch_execnz .LBB0_95

.LBB0_136:
	v_add_u32_e32 v33, s70, v32
	v_cmp_gt_i32_e32 vcc, s28, v33
	v_readlane_b32 s8, v252, 62
	v_readlane_b32 s10, v253, 2
	v_cndmask_b32_e32 v38, v32, v33, vcc
	v_ashrrev_i32_e32 v39, 31, v38
	v_lshlrev_b64 v[48:49], 11, v[38:39]
	v_readlane_b32 s9, v252, 63
	v_readlane_b32 s11, v253, 3
	s_nop 0
	v_lshl_add_u64 v[38:39], s[8:9], 0, v[48:49]
	v_lshl_add_u64 v[48:49], s[10:11], 0, v[48:49]
	v_lshl_add_u64 v[46:47], v[38:39], 0, v[188:189]
	v_lshl_add_u64 v[48:49], v[48:49], 0, v[188:189]
	global_load_dwordx2 v[38:39], v[46:47], off offset:1536
	global_load_dwordx2 v[42:43], v[46:47], off offset:1024
	global_load_dwordx2 v[44:45], v[46:47], off offset:512
	s_nop 0
	global_load_dwordx2 v[46:47], v[46:47], off
	s_nop 0
	global_load_dwordx2 v[54:55], v[48:49], off offset:1536
	global_load_dwordx2 v[56:57], v[48:49], off offset:1024
	global_load_dwordx2 v[60:61], v[48:49], off offset:512
	global_load_dwordx2 v[62:63], v[48:49], off
	v_lshl_add_u64 v[52:53], s[8:9], 0, v[188:189]
	v_readlane_b32 s8, v254, 32
	v_readlane_b32 s9, v254, 33
	v_lshl_add_u64 v[48:49], s[10:11], 0, v[188:189]
	s_nop 0
	v_lshl_add_u64 v[58:59], s[8:9], 0, v[188:189]
	s_mov_b64 s[8:9], 0
	s_waitcnt vmcnt(0)
	s_branch .LBB0_139
.LBB0_139:
	v_add_u32_e32 v89, s71, v32
	v_cmp_gt_i32_e32 vcc, s28, v89
	s_nop 1
	v_cndmask_b32_e32 v66, v32, v89, vcc
	v_ashrrev_i32_e32 v67, 31, v66
	v_lshlrev_b64 v[66:67], 11, v[66:67]
	v_lshl_add_u64 v[72:73], v[48:49], 0, v[66:67]
	s_waitcnt lgkmcnt(0)
	v_lshl_add_u64 v[80:81], v[52:53], 0, v[66:67]
	global_load_dwordx2 v[66:67], v[72:73], off
	global_load_dwordx2 v[68:69], v[72:73], off offset:512
	global_load_dwordx2 v[70:71], v[72:73], off offset:1024
	s_nop 0
	global_load_dwordx2 v[72:73], v[72:73], off offset:1536
	s_nop 0
	global_load_dwordx2 v[74:75], v[80:81], off
	global_load_dwordx2 v[76:77], v[80:81], off offset:512
	global_load_dwordx2 v[78:79], v[80:81], off offset:1024
	s_nop 0
	global_load_dwordx2 v[80:81], v[80:81], off offset:1536
	s_waitcnt vmcnt(32)
	v_lshlrev_b32_e32 v100, 16, v86
	v_and_b32_e32 v101, 0xffff0000, v86
	v_lshlrev_b32_e32 v96, 16, v87
	v_and_b32_e32 v97, 0xffff0000, v87
	v_pk_mul_f32 v[86:87], v[100:101], v[100:101]
	v_pk_mul_f32 v[98:99], v[96:97], v[96:97]
	v_add_f32_e32 v86, v86, v87
	v_lshlrev_b32_e32 v106, 16, v84
	v_and_b32_e32 v107, 0xffff0000, v84
	v_add_f32_e32 v86, v98, v86
	v_lshlrev_b32_e32 v102, 16, v85
	v_and_b32_e32 v103, 0xffff0000, v85
	v_pk_mul_f32 v[84:85], v[106:107], v[106:107]
	v_add_f32_e32 v86, v99, v86
	v_add_f32_e32 v84, v84, v86
	v_pk_mul_f32 v[104:105], v[102:103], v[102:103]
	v_add_f32_e32 v84, v85, v84
	v_lshlrev_b32_e32 v112, 16, v82
	v_and_b32_e32 v113, 0xffff0000, v82
	v_add_f32_e32 v84, v104, v84
	v_lshlrev_b32_e32 v108, 16, v83
	v_and_b32_e32 v109, 0xffff0000, v83
	v_pk_mul_f32 v[82:83], v[112:113], v[112:113]
	v_add_f32_e32 v84, v105, v84
	v_add_f32_e32 v82, v82, v84
	v_pk_mul_f32 v[110:111], v[108:109], v[108:109]
	v_add_f32_e32 v82, v83, v82
	v_lshlrev_b32_e32 v114, 16, v64
	v_and_b32_e32 v115, 0xffff0000, v64
	v_add_f32_e32 v82, v110, v82
	v_and_b32_e32 v33, 64, v207
	v_and_b32_e32 v95, 0xffff0000, v65
	v_lshlrev_b32_e32 v94, 16, v65
	v_pk_mul_f32 v[64:65], v[114:115], v[114:115]
	v_add_f32_e32 v82, v111, v82
	v_add_u32_e32 v116, 64, v33
	v_xor_b32_e32 v33, 32, v207
	v_add_f32_e32 v64, v64, v82
	v_cmp_lt_i32_e32 vcc, v33, v116
	v_pk_mul_f32 v[92:93], v[94:95], v[94:95]
	v_add_f32_e32 v64, v65, v64
	v_cndmask_b32_e32 v33, v207, v33, vcc
	v_add_f32_e32 v64, v92, v64
	v_lshlrev_b32_e32 v33, 2, v33
	v_add_f32_e32 v64, v93, v64
	ds_bpermute_b32 v65, v33, v64
	v_xor_b32_e32 v88, 16, v207
	v_cmp_lt_i32_e32 vcc, v88, v116
	v_xor_b32_e32 v90, 8, v207
	v_xor_b32_e32 v91, 4, v207
	v_cndmask_b32_e32 v88, v207, v88, vcc
	v_lshlrev_b32_e32 v88, 2, v88
	s_waitcnt lgkmcnt(0)
	v_add_f32_e32 v64, v64, v65
	ds_bpermute_b32 v65, v88, v64
	v_cmp_lt_i32_e32 vcc, v90, v116
	v_and_b32_e32 v99, 0xffff0000, v37
	v_lshlrev_b32_e32 v98, 16, v37
	v_cndmask_b32_e32 v90, v207, v90, vcc
	v_lshlrev_b32_e32 v90, 2, v90
	s_waitcnt lgkmcnt(0)
	v_add_f32_e32 v64, v64, v65
	ds_bpermute_b32 v65, v90, v64
	v_cmp_lt_i32_e32 vcc, v91, v116
	v_lshlrev_b32_e32 v104, 16, v40
	v_and_b32_e32 v105, 0xffff0000, v40
	v_cndmask_b32_e32 v82, v207, v91, vcc
	v_lshlrev_b32_e32 v91, 2, v82
	s_waitcnt lgkmcnt(0)
	v_add_f32_e32 v83, v64, v65
	ds_bpermute_b32 v84, v91, v83
	v_xor_b32_e32 v82, 2, v207
	v_cmp_lt_i32_e32 vcc, v82, v116
	v_lshlrev_b32_e32 v64, 16, v51
	v_and_b32_e32 v65, 0xffff0000, v51
	v_cndmask_b32_e32 v82, v207, v82, vcc
	v_lshlrev_b32_e32 v92, 2, v82
	s_waitcnt lgkmcnt(0)
	v_add_f32_e32 v37, v83, v84
	ds_bpermute_b32 v84, v92, v37
	v_xor_b32_e32 v82, 1, v207
	v_cmp_lt_i32_e32 vcc, v82, v116
	v_and_b32_e32 v83, 0xffff0000, v50
	v_and_b32_e32 v51, 0xffff0000, v41
	v_cndmask_b32_e32 v82, v207, v82, vcc
	v_lshlrev_b32_e32 v93, 2, v82
	s_waitcnt lgkmcnt(0)
	v_add_f32_e32 v37, v37, v84
	ds_bpermute_b32 v84, v93, v37
	v_lshlrev_b32_e32 v82, 16, v50
	v_lshlrev_b32_e32 v50, 16, v41
	v_lshlrev_b32_e32 v40, 16, v35
	v_and_b32_e32 v41, 0xffff0000, v35
	s_waitcnt lgkmcnt(0)
	v_add_f32_e32 v35, v37, v84
	v_fmamk_f32 v35, v35, 0x3a800000, v205
	v_mul_f32_e32 v37, 0x4b800000, v35
	v_cmp_gt_f32_e32 vcc, s30, v35
	v_lshlrev_b32_e32 v110, 16, v34
	v_and_b32_e32 v111, 0xffff0000, v34
	v_cndmask_b32_e32 v35, v35, v37, vcc
	v_rsq_f32_e32 v37, v35
	v_lshlrev_b32_e32 v34, 16, v36
	v_and_b32_e32 v35, 0xffff0000, v36
	v_mul_f32_e32 v36, 0x45800000, v37
	v_cndmask_b32_e32 v36, v37, v36, vcc
	v_pk_mul_f32 v[84:85], v[36:37], v[100:101] op_sel_hi:[0,1]
	v_pk_fma_f32 v[86:87], v[0:1], v[84:85], v[82:83]
	v_pk_mul_f32 v[82:83], v[36:37], v[96:97] op_sel_hi:[0,1]
	v_pk_fma_f32 v[84:85], v[2:3], v[82:83], v[64:65]
	v_pk_mul_f32 v[64:65], v[36:37], v[106:107] op_sel_hi:[0,1]
	v_pk_fma_f32 v[82:83], v[4:5], v[64:65], v[104:105]
	v_pk_mul_f32 v[64:65], v[36:37], v[102:103] op_sel_hi:[0,1]
	v_pk_mul_f32 v[96:97], v[36:37], v[108:109] op_sel_hi:[0,1]
	v_pk_fma_f32 v[64:65], v[6:7], v[64:65], v[50:51]
	v_pk_mul_f32 v[50:51], v[36:37], v[112:113] op_sel_hi:[0,1]
	v_pk_fma_f32 v[40:41], v[10:11], v[96:97], v[40:41]
	v_pk_mul_f32 v[96:97], v[36:37], v[114:115] op_sel_hi:[0,1]
	v_pk_mul_f32 v[36:37], v[36:37], v[94:95] op_sel_hi:[0,1]
	v_pk_fma_f32 v[50:51], v[8:9], v[50:51], v[110:111]
	v_pk_fma_f32 v[34:35], v[12:13], v[96:97], v[34:35]
	s_and_b64 vcc, exec, s[4:5]
	v_pk_fma_f32 v[36:37], v[14:15], v[36:37], v[98:99]
	s_cbranch_vccz .Lrp139_n2_0
	v_mov_b32_e32 v88, 1.0
	s_branch .Lrp139_st_0

.Lrp139_st_0:
	v_ashrrev_i32_e32 v33, 31, v32
	v_lshlrev_b64 v[32:33], 11, v[32:33]
	v_lshl_add_u64 v[90:91], v[48:49], 0, v[32:33]
	v_cvt_pk_bf16_f32 v92, v86, v87
	v_cvt_pk_bf16_f32 v93, v84, v85
	global_store_dwordx2 v[90:91], v[92:93], off
	v_cvt_pk_bf16_f32 v92, v82, v83
	v_cvt_pk_bf16_f32 v93, v64, v65
	global_store_dwordx2 v[90:91], v[92:93], off offset:512
	v_cvt_pk_bf16_f32 v92, v50, v51
	v_cvt_pk_bf16_f32 v93, v40, v41
	global_store_dwordx2 v[90:91], v[92:93], off offset:1024
	v_cvt_pk_bf16_f32 v92, v34, v35
	v_cvt_pk_bf16_f32 v93, v36, v37
	v_pk_mul_f32 v[86:87], v[86:87], v[88:89] op_sel_hi:[1,0]
	v_pk_mul_f32 v[84:85], v[84:85], v[88:89] op_sel_hi:[1,0]
	v_pk_mul_f32 v[82:83], v[82:83], v[88:89] op_sel_hi:[1,0]
	v_pk_mul_f32 v[64:65], v[64:65], v[88:89] op_sel_hi:[1,0]
	v_pk_mul_f32 v[50:51], v[50:51], v[88:89] op_sel_hi:[1,0]
	v_pk_mul_f32 v[40:41], v[40:41], v[88:89] op_sel_hi:[1,0]
	v_pk_mul_f32 v[34:35], v[34:35], v[88:89] op_sel_hi:[1,0]
	v_pk_mul_f32 v[36:37], v[36:37], v[88:89] op_sel_hi:[1,0]
	v_pk_mul_f32 v[86:87], v[16:17], v[86:87]
	v_pk_mul_f32 v[84:85], v[18:19], v[84:85]
	v_pk_mul_f32 v[82:83], v[20:21], v[82:83]
	v_pk_mul_f32 v[64:65], v[22:23], v[64:65]
	v_pk_mul_f32 v[50:51], v[24:25], v[50:51]
	v_pk_mul_f32 v[40:41], v[26:27], v[40:41]
	v_pk_mul_f32 v[34:35], v[28:29], v[34:35]
	v_pk_mul_f32 v[36:37], v[30:31], v[36:37]
	v_lshl_add_u64 v[32:33], v[58:59], 0, v[32:33]
	v_cvt_pk_bf16_f32 v86, v86, v87
	v_cvt_pk_bf16_f32 v87, v84, v85
	v_cvt_pk_bf16_f32 v82, v82, v83
	v_cvt_pk_bf16_f32 v83, v64, v65
	v_cvt_pk_bf16_f32 v50, v50, v51
	v_cvt_pk_bf16_f32 v51, v40, v41
	v_cvt_pk_bf16_f32 v34, v34, v35
	v_cvt_pk_bf16_f32 v35, v36, v37
	global_store_dwordx2 v[90:91], v[92:93], off offset:1536
	global_store_dwordx2 v[32:33], v[86:87], off
	global_store_dwordx2 v[32:33], v[82:83], off offset:512
	global_store_dwordx2 v[32:33], v[50:51], off offset:1024
	global_store_dwordx2 v[32:33], v[34:35], off offset:1536
	v_subrev_u32_e32 v32, s70, v89
	v_cmp_lt_i32_e32 vcc, s31, v32
	s_or_b64 s[8:9], vcc, s[8:9]
	s_andn2_b64 exec, exec, s[8:9]
	s_cbranch_execz .LBB0_141
.Lrp139_top1:
	v_add_u32_e32 v89, s71, v32
	v_cmp_gt_i32_e32 vcc, s28, v89
	s_nop 1
	v_cndmask_b32_e32 v50, v32, v89, vcc
	v_ashrrev_i32_e32 v51, 31, v50
	v_lshlrev_b64 v[50:51], 11, v[50:51]
	v_lshl_add_u64 v[36:37], v[48:49], 0, v[50:51]
	s_waitcnt lgkmcnt(0)
	v_lshl_add_u64 v[64:65], v[52:53], 0, v[50:51]
	global_load_dwordx2 v[50:51], v[36:37], off
	global_load_dwordx2 v[40:41], v[36:37], off offset:512
	global_load_dwordx2 v[34:35], v[36:37], off offset:1024
	s_nop 0
	global_load_dwordx2 v[36:37], v[36:37], off offset:1536
	s_nop 0
	global_load_dwordx2 v[86:87], v[64:65], off
	global_load_dwordx2 v[84:85], v[64:65], off offset:512
	global_load_dwordx2 v[82:83], v[64:65], off offset:1024
	s_nop 0
	global_load_dwordx2 v[64:65], v[64:65], off offset:1536
	s_waitcnt vmcnt(32)
	v_lshlrev_b32_e32 v100, 16, v46
	v_and_b32_e32 v101, 0xffff0000, v46
	v_lshlrev_b32_e32 v96, 16, v47
	v_and_b32_e32 v97, 0xffff0000, v47
	v_pk_mul_f32 v[46:47], v[100:101], v[100:101]
	v_pk_mul_f32 v[98:99], v[96:97], v[96:97]
	v_add_f32_e32 v46, v46, v47
	v_lshlrev_b32_e32 v106, 16, v44
	v_and_b32_e32 v107, 0xffff0000, v44
	v_add_f32_e32 v46, v98, v46
	v_lshlrev_b32_e32 v102, 16, v45
	v_and_b32_e32 v103, 0xffff0000, v45
	v_pk_mul_f32 v[44:45], v[106:107], v[106:107]
	v_add_f32_e32 v46, v99, v46
	v_add_f32_e32 v44, v44, v46
	v_pk_mul_f32 v[104:105], v[102:103], v[102:103]
	v_add_f32_e32 v44, v45, v44
	v_lshlrev_b32_e32 v112, 16, v42
	v_and_b32_e32 v113, 0xffff0000, v42
	v_add_f32_e32 v44, v104, v44
	v_lshlrev_b32_e32 v108, 16, v43
	v_and_b32_e32 v109, 0xffff0000, v43
	v_pk_mul_f32 v[42:43], v[112:113], v[112:113]
	v_add_f32_e32 v44, v105, v44
	v_add_f32_e32 v42, v42, v44
	v_pk_mul_f32 v[110:111], v[108:109], v[108:109]
	v_add_f32_e32 v42, v43, v42
	v_lshlrev_b32_e32 v114, 16, v38
	v_and_b32_e32 v115, 0xffff0000, v38
	v_add_f32_e32 v42, v110, v42
	v_and_b32_e32 v33, 64, v207
	v_and_b32_e32 v95, 0xffff0000, v39
	v_lshlrev_b32_e32 v94, 16, v39
	v_pk_mul_f32 v[38:39], v[114:115], v[114:115]
	v_add_f32_e32 v42, v111, v42
	v_add_u32_e32 v116, 64, v33
	v_xor_b32_e32 v33, 32, v207
	v_add_f32_e32 v38, v38, v42
	v_cmp_lt_i32_e32 vcc, v33, v116
	v_pk_mul_f32 v[92:93], v[94:95], v[94:95]
	v_add_f32_e32 v38, v39, v38
	v_cndmask_b32_e32 v33, v207, v33, vcc
	v_add_f32_e32 v38, v92, v38
	v_lshlrev_b32_e32 v33, 2, v33
	v_add_f32_e32 v38, v93, v38
	ds_bpermute_b32 v39, v33, v38
	v_xor_b32_e32 v88, 16, v207
	v_cmp_lt_i32_e32 vcc, v88, v116
	v_xor_b32_e32 v90, 8, v207
	v_xor_b32_e32 v91, 4, v207
	v_cndmask_b32_e32 v88, v207, v88, vcc
	v_lshlrev_b32_e32 v88, 2, v88
	s_waitcnt lgkmcnt(0)
	v_add_f32_e32 v38, v38, v39
	ds_bpermute_b32 v39, v88, v38
	v_cmp_lt_i32_e32 vcc, v90, v116
	v_and_b32_e32 v99, 0xffff0000, v55
	v_lshlrev_b32_e32 v98, 16, v55
	v_cndmask_b32_e32 v90, v207, v90, vcc
	v_lshlrev_b32_e32 v90, 2, v90
	s_waitcnt lgkmcnt(0)
	v_add_f32_e32 v38, v38, v39
	ds_bpermute_b32 v39, v90, v38
	v_cmp_lt_i32_e32 vcc, v91, v116
	v_lshlrev_b32_e32 v104, 16, v60
	v_and_b32_e32 v105, 0xffff0000, v60
	v_cndmask_b32_e32 v42, v207, v91, vcc
	v_lshlrev_b32_e32 v91, 2, v42
	s_waitcnt lgkmcnt(0)
	v_add_f32_e32 v43, v38, v39
	ds_bpermute_b32 v44, v91, v43
	v_xor_b32_e32 v42, 2, v207
	v_cmp_lt_i32_e32 vcc, v42, v116
	v_lshlrev_b32_e32 v38, 16, v63
	v_and_b32_e32 v39, 0xffff0000, v63
	v_cndmask_b32_e32 v42, v207, v42, vcc
	v_lshlrev_b32_e32 v92, 2, v42
	s_waitcnt lgkmcnt(0)
	v_add_f32_e32 v55, v43, v44
	ds_bpermute_b32 v44, v92, v55
	v_xor_b32_e32 v42, 1, v207
	v_cmp_lt_i32_e32 vcc, v42, v116
	v_and_b32_e32 v43, 0xffff0000, v62
	v_and_b32_e32 v63, 0xffff0000, v61
	v_cndmask_b32_e32 v42, v207, v42, vcc
	v_lshlrev_b32_e32 v93, 2, v42
	s_waitcnt lgkmcnt(0)
	v_add_f32_e32 v55, v55, v44
	ds_bpermute_b32 v44, v93, v55
	v_lshlrev_b32_e32 v42, 16, v62
	v_lshlrev_b32_e32 v62, 16, v61
	v_lshlrev_b32_e32 v60, 16, v57
	v_and_b32_e32 v61, 0xffff0000, v57
	s_waitcnt lgkmcnt(0)
	v_add_f32_e32 v57, v55, v44
	v_fmamk_f32 v57, v57, 0x3a800000, v205
	v_mul_f32_e32 v55, 0x4b800000, v57
	v_cmp_gt_f32_e32 vcc, s30, v57
	v_lshlrev_b32_e32 v110, 16, v56
	v_and_b32_e32 v111, 0xffff0000, v56
	v_cndmask_b32_e32 v57, v57, v55, vcc
	v_rsq_f32_e32 v55, v57
	v_lshlrev_b32_e32 v56, 16, v54
	v_and_b32_e32 v57, 0xffff0000, v54
	v_mul_f32_e32 v54, 0x45800000, v55
	v_cndmask_b32_e32 v54, v55, v54, vcc
	v_pk_mul_f32 v[44:45], v[54:55], v[100:101] op_sel_hi:[0,1]
	v_pk_fma_f32 v[46:47], v[0:1], v[44:45], v[42:43]
	v_pk_mul_f32 v[42:43], v[54:55], v[96:97] op_sel_hi:[0,1]
	v_pk_fma_f32 v[44:45], v[2:3], v[42:43], v[38:39]
	v_pk_mul_f32 v[38:39], v[54:55], v[106:107] op_sel_hi:[0,1]
	v_pk_fma_f32 v[42:43], v[4:5], v[38:39], v[104:105]
	v_pk_mul_f32 v[38:39], v[54:55], v[102:103] op_sel_hi:[0,1]
	v_pk_mul_f32 v[96:97], v[54:55], v[108:109] op_sel_hi:[0,1]
	v_pk_fma_f32 v[38:39], v[6:7], v[38:39], v[62:63]
	v_pk_mul_f32 v[62:63], v[54:55], v[112:113] op_sel_hi:[0,1]
	v_pk_fma_f32 v[60:61], v[10:11], v[96:97], v[60:61]
	v_pk_mul_f32 v[96:97], v[54:55], v[114:115] op_sel_hi:[0,1]
	v_pk_mul_f32 v[54:55], v[54:55], v[94:95] op_sel_hi:[0,1]
	v_pk_fma_f32 v[62:63], v[8:9], v[62:63], v[110:111]
	v_pk_fma_f32 v[56:57], v[12:13], v[96:97], v[56:57]
	s_and_b64 vcc, exec, s[4:5]
	v_pk_fma_f32 v[54:55], v[14:15], v[54:55], v[98:99]
	s_cbranch_vccz .Lrp139_n2_1
	v_mov_b32_e32 v88, 1.0
	s_branch .Lrp139_st_1
.Lrp139_n2_1:
	v_pk_mul_f32 v[94:95], v[46:47], v[46:47]
	v_pk_mul_f32 v[96:97], v[44:45], v[44:45]
	v_add_f32_e32 v94, v94, v95
	v_add_f32_e32 v94, v96, v94
	v_pk_mul_f32 v[98:99], v[42:43], v[42:43]
	v_add_f32_e32 v94, v97, v94
	v_add_f32_e32 v94, v98, v94
	v_pk_mul_f32 v[100:101], v[38:39], v[38:39]
	v_add_f32_e32 v94, v99, v94
	v_add_f32_e32 v94, v100, v94
	v_pk_mul_f32 v[102:103], v[62:63], v[62:63]
	v_add_f32_e32 v94, v101, v94
	v_add_f32_e32 v94, v102, v94
	v_pk_mul_f32 v[104:105], v[60:61], v[60:61]
	v_add_f32_e32 v94, v103, v94
	v_add_f32_e32 v94, v104, v94
	v_pk_mul_f32 v[106:107], v[56:57], v[56:57]
	v_add_f32_e32 v94, v105, v94
	v_add_f32_e32 v94, v106, v94
	v_pk_mul_f32 v[108:109], v[54:55], v[54:55]
	v_add_f32_e32 v94, v107, v94
	v_add_f32_e32 v94, v108, v94
	v_add_f32_e32 v94, v109, v94
	ds_bpermute_b32 v33, v33, v94
	s_waitcnt lgkmcnt(0)
	v_add_f32_e32 v33, v94, v33
	ds_bpermute_b32 v88, v88, v33
	s_waitcnt lgkmcnt(0)
	v_add_f32_e32 v33, v33, v88
	ds_bpermute_b32 v88, v90, v33
	s_waitcnt lgkmcnt(0)
	v_add_f32_e32 v33, v33, v88
	ds_bpermute_b32 v88, v91, v33
	s_waitcnt lgkmcnt(0)
	v_add_f32_e32 v33, v33, v88
	ds_bpermute_b32 v88, v92, v33
	s_waitcnt lgkmcnt(0)
	v_add_f32_e32 v33, v33, v88
	ds_bpermute_b32 v88, v93, v33
	s_waitcnt lgkmcnt(0)
	v_add_f32_e32 v33, v33, v88
	v_fmamk_f32 v33, v33, 0x3a800000, v205
	v_mul_f32_e32 v88, 0x4b800000, v33
	v_cmp_gt_f32_e32 vcc, s30, v33
	s_nop 1
	v_cndmask_b32_e32 v33, v33, v88, vcc
	v_rsq_f32_e32 v33, v33
	s_nop 0
	v_mul_f32_e32 v88, 0x45800000, v33
	v_cndmask_b32_e32 v88, v33, v88, vcc
.Lrp139_st_1:
	v_ashrrev_i32_e32 v33, 31, v32
	v_lshlrev_b64 v[32:33], 11, v[32:33]
	v_lshl_add_u64 v[90:91], v[48:49], 0, v[32:33]
	v_cvt_pk_bf16_f32 v92, v46, v47
	v_cvt_pk_bf16_f32 v93, v44, v45
	global_store_dwordx2 v[90:91], v[92:93], off
	v_cvt_pk_bf16_f32 v92, v42, v43
	v_cvt_pk_bf16_f32 v93, v38, v39
	global_store_dwordx2 v[90:91], v[92:93], off offset:512
	v_cvt_pk_bf16_f32 v92, v62, v63
	v_cvt_pk_bf16_f32 v93, v60, v61
	global_store_dwordx2 v[90:91], v[92:93], off offset:1024
	v_cvt_pk_bf16_f32 v92, v56, v57
	v_cvt_pk_bf16_f32 v93, v54, v55
	v_pk_mul_f32 v[46:47], v[46:47], v[88:89] op_sel_hi:[1,0]
	v_pk_mul_f32 v[44:45], v[44:45], v[88:89] op_sel_hi:[1,0]
	v_pk_mul_f32 v[42:43], v[42:43], v[88:89] op_sel_hi:[1,0]
	v_pk_mul_f32 v[38:39], v[38:39], v[88:89] op_sel_hi:[1,0]
	v_pk_mul_f32 v[62:63], v[62:63], v[88:89] op_sel_hi:[1,0]
	v_pk_mul_f32 v[60:61], v[60:61], v[88:89] op_sel_hi:[1,0]
	v_pk_mul_f32 v[56:57], v[56:57], v[88:89] op_sel_hi:[1,0]
	v_pk_mul_f32 v[54:55], v[54:55], v[88:89] op_sel_hi:[1,0]
	v_pk_mul_f32 v[46:47], v[16:17], v[46:47]
	v_pk_mul_f32 v[44:45], v[18:19], v[44:45]
	v_pk_mul_f32 v[42:43], v[20:21], v[42:43]
	v_pk_mul_f32 v[38:39], v[22:23], v[38:39]
	v_pk_mul_f32 v[62:63], v[24:25], v[62:63]
	v_pk_mul_f32 v[60:61], v[26:27], v[60:61]
	v_pk_mul_f32 v[56:57], v[28:29], v[56:57]
	v_pk_mul_f32 v[54:55], v[30:31], v[54:55]
	v_lshl_add_u64 v[32:33], v[58:59], 0, v[32:33]
	v_cvt_pk_bf16_f32 v46, v46, v47
	v_cvt_pk_bf16_f32 v47, v44, v45
	v_cvt_pk_bf16_f32 v42, v42, v43
	v_cvt_pk_bf16_f32 v43, v38, v39
	v_cvt_pk_bf16_f32 v62, v62, v63
	v_cvt_pk_bf16_f32 v63, v60, v61
	v_cvt_pk_bf16_f32 v56, v56, v57
	v_cvt_pk_bf16_f32 v57, v54, v55
	global_store_dwordx2 v[90:91], v[92:93], off offset:1536
	global_store_dwordx2 v[32:33], v[46:47], off
	global_store_dwordx2 v[32:33], v[42:43], off offset:512
	global_store_dwordx2 v[32:33], v[62:63], off offset:1024
	global_store_dwordx2 v[32:33], v[56:57], off offset:1536
	v_subrev_u32_e32 v32, s70, v89
	v_cmp_lt_i32_e32 vcc, s31, v32
	s_or_b64 s[8:9], vcc, s[8:9]
	s_andn2_b64 exec, exec, s[8:9]
	s_cbranch_execz .LBB0_141
.Lrp139_top2:
	v_add_u32_e32 v89, s71, v32
	v_cmp_gt_i32_e32 vcc, s28, v89
	s_nop 1
	v_cndmask_b32_e32 v62, v32, v89, vcc
	v_ashrrev_i32_e32 v63, 31, v62
	v_lshlrev_b64 v[62:63], 11, v[62:63]
	v_lshl_add_u64 v[54:55], v[48:49], 0, v[62:63]
	s_waitcnt lgkmcnt(0)
	v_lshl_add_u64 v[38:39], v[52:53], 0, v[62:63]
	global_load_dwordx2 v[62:63], v[54:55], off
	global_load_dwordx2 v[60:61], v[54:55], off offset:512
	global_load_dwordx2 v[56:57], v[54:55], off offset:1024
	s_nop 0
	global_load_dwordx2 v[54:55], v[54:55], off offset:1536
	s_nop 0
	global_load_dwordx2 v[46:47], v[38:39], off
	global_load_dwordx2 v[44:45], v[38:39], off offset:512
	global_load_dwordx2 v[42:43], v[38:39], off offset:1024
	s_nop 0
	global_load_dwordx2 v[38:39], v[38:39], off offset:1536
	s_waitcnt vmcnt(32)
	v_lshlrev_b32_e32 v100, 16, v74
	v_and_b32_e32 v101, 0xffff0000, v74
	v_lshlrev_b32_e32 v96, 16, v75
	v_and_b32_e32 v97, 0xffff0000, v75
	v_pk_mul_f32 v[74:75], v[100:101], v[100:101]
	v_pk_mul_f32 v[98:99], v[96:97], v[96:97]
	v_add_f32_e32 v74, v74, v75
	v_lshlrev_b32_e32 v106, 16, v76
	v_and_b32_e32 v107, 0xffff0000, v76
	v_add_f32_e32 v74, v98, v74
	v_lshlrev_b32_e32 v102, 16, v77
	v_and_b32_e32 v103, 0xffff0000, v77
	v_pk_mul_f32 v[76:77], v[106:107], v[106:107]
	v_add_f32_e32 v74, v99, v74
	v_add_f32_e32 v76, v76, v74
	v_pk_mul_f32 v[104:105], v[102:103], v[102:103]
	v_add_f32_e32 v76, v77, v76
	v_lshlrev_b32_e32 v112, 16, v78
	v_and_b32_e32 v113, 0xffff0000, v78
	v_add_f32_e32 v76, v104, v76
	v_lshlrev_b32_e32 v108, 16, v79
	v_and_b32_e32 v109, 0xffff0000, v79
	v_pk_mul_f32 v[78:79], v[112:113], v[112:113]
	v_add_f32_e32 v76, v105, v76
	v_add_f32_e32 v78, v78, v76
	v_pk_mul_f32 v[110:111], v[108:109], v[108:109]
	v_add_f32_e32 v78, v79, v78
	v_lshlrev_b32_e32 v114, 16, v80
	v_and_b32_e32 v115, 0xffff0000, v80
	v_add_f32_e32 v78, v110, v78
	v_and_b32_e32 v33, 64, v207
	v_and_b32_e32 v95, 0xffff0000, v81
	v_lshlrev_b32_e32 v94, 16, v81
	v_pk_mul_f32 v[80:81], v[114:115], v[114:115]
	v_add_f32_e32 v78, v111, v78
	v_add_u32_e32 v116, 64, v33
	v_xor_b32_e32 v33, 32, v207
	v_add_f32_e32 v80, v80, v78
	v_cmp_lt_i32_e32 vcc, v33, v116
	v_pk_mul_f32 v[92:93], v[94:95], v[94:95]
	v_add_f32_e32 v80, v81, v80
	v_cndmask_b32_e32 v33, v207, v33, vcc
	v_add_f32_e32 v80, v92, v80
	v_lshlrev_b32_e32 v33, 2, v33
	v_add_f32_e32 v80, v93, v80
	ds_bpermute_b32 v81, v33, v80
	v_xor_b32_e32 v88, 16, v207
	v_cmp_lt_i32_e32 vcc, v88, v116
	v_xor_b32_e32 v90, 8, v207
	v_xor_b32_e32 v91, 4, v207
	v_cndmask_b32_e32 v88, v207, v88, vcc
	v_lshlrev_b32_e32 v88, 2, v88
	s_waitcnt lgkmcnt(0)
	v_add_f32_e32 v80, v80, v81
	ds_bpermute_b32 v81, v88, v80
	v_cmp_lt_i32_e32 vcc, v90, v116
	v_and_b32_e32 v99, 0xffff0000, v73
	v_lshlrev_b32_e32 v98, 16, v73
	v_cndmask_b32_e32 v90, v207, v90, vcc
	v_lshlrev_b32_e32 v90, 2, v90
	s_waitcnt lgkmcnt(0)
	v_add_f32_e32 v80, v80, v81
	ds_bpermute_b32 v81, v90, v80
	v_cmp_lt_i32_e32 vcc, v91, v116
	v_lshlrev_b32_e32 v104, 16, v68
	v_and_b32_e32 v105, 0xffff0000, v68
	v_cndmask_b32_e32 v78, v207, v91, vcc
	v_lshlrev_b32_e32 v91, 2, v78
	s_waitcnt lgkmcnt(0)
	v_add_f32_e32 v79, v80, v81
	ds_bpermute_b32 v76, v91, v79
	v_xor_b32_e32 v78, 2, v207
	v_cmp_lt_i32_e32 vcc, v78, v116
	v_lshlrev_b32_e32 v80, 16, v67
	v_and_b32_e32 v81, 0xffff0000, v67
	v_cndmask_b32_e32 v78, v207, v78, vcc
	v_lshlrev_b32_e32 v92, 2, v78
	s_waitcnt lgkmcnt(0)
	v_add_f32_e32 v73, v79, v76
	ds_bpermute_b32 v76, v92, v73
	v_xor_b32_e32 v78, 1, v207
	v_cmp_lt_i32_e32 vcc, v78, v116
	v_and_b32_e32 v79, 0xffff0000, v66
	v_and_b32_e32 v67, 0xffff0000, v69
	v_cndmask_b32_e32 v78, v207, v78, vcc
	v_lshlrev_b32_e32 v93, 2, v78
	s_waitcnt lgkmcnt(0)
	v_add_f32_e32 v73, v73, v76
	ds_bpermute_b32 v76, v93, v73
	v_lshlrev_b32_e32 v78, 16, v66
	v_lshlrev_b32_e32 v66, 16, v69
	v_lshlrev_b32_e32 v68, 16, v71
	v_and_b32_e32 v69, 0xffff0000, v71
	s_waitcnt lgkmcnt(0)
	v_add_f32_e32 v71, v73, v76
	v_fmamk_f32 v71, v71, 0x3a800000, v205
	v_mul_f32_e32 v73, 0x4b800000, v71
	v_cmp_gt_f32_e32 vcc, s30, v71
	v_lshlrev_b32_e32 v110, 16, v70
	v_and_b32_e32 v111, 0xffff0000, v70
	v_cndmask_b32_e32 v71, v71, v73, vcc
	v_rsq_f32_e32 v73, v71
	v_lshlrev_b32_e32 v70, 16, v72
	v_and_b32_e32 v71, 0xffff0000, v72
	v_mul_f32_e32 v72, 0x45800000, v73
	v_cndmask_b32_e32 v72, v73, v72, vcc
	v_pk_mul_f32 v[76:77], v[72:73], v[100:101] op_sel_hi:[0,1]
	v_pk_fma_f32 v[74:75], v[0:1], v[76:77], v[78:79]
	v_pk_mul_f32 v[78:79], v[72:73], v[96:97] op_sel_hi:[0,1]
	v_pk_fma_f32 v[76:77], v[2:3], v[78:79], v[80:81]
	v_pk_mul_f32 v[80:81], v[72:73], v[106:107] op_sel_hi:[0,1]
	v_pk_fma_f32 v[78:79], v[4:5], v[80:81], v[104:105]
	v_pk_mul_f32 v[80:81], v[72:73], v[102:103] op_sel_hi:[0,1]
	v_pk_mul_f32 v[96:97], v[72:73], v[108:109] op_sel_hi:[0,1]
	v_pk_fma_f32 v[80:81], v[6:7], v[80:81], v[66:67]
	v_pk_mul_f32 v[66:67], v[72:73], v[112:113] op_sel_hi:[0,1]
	v_pk_fma_f32 v[68:69], v[10:11], v[96:97], v[68:69]
	v_pk_mul_f32 v[96:97], v[72:73], v[114:115] op_sel_hi:[0,1]
	v_pk_mul_f32 v[72:73], v[72:73], v[94:95] op_sel_hi:[0,1]
	v_pk_fma_f32 v[66:67], v[8:9], v[66:67], v[110:111]
	v_pk_fma_f32 v[70:71], v[12:13], v[96:97], v[70:71]
	s_and_b64 vcc, exec, s[4:5]
	v_pk_fma_f32 v[72:73], v[14:15], v[72:73], v[98:99]
	s_cbranch_vccz .Lrp139_n2_2
	v_mov_b32_e32 v88, 1.0
	s_branch .Lrp139_st_2
.Lrp139_n2_2:
	v_pk_mul_f32 v[94:95], v[74:75], v[74:75]
	v_pk_mul_f32 v[96:97], v[76:77], v[76:77]
	v_add_f32_e32 v94, v94, v95
	v_add_f32_e32 v94, v96, v94
	v_pk_mul_f32 v[98:99], v[78:79], v[78:79]
	v_add_f32_e32 v94, v97, v94
	v_add_f32_e32 v94, v98, v94
	v_pk_mul_f32 v[100:101], v[80:81], v[80:81]
	v_add_f32_e32 v94, v99, v94
	v_add_f32_e32 v94, v100, v94
	v_pk_mul_f32 v[102:103], v[66:67], v[66:67]
	v_add_f32_e32 v94, v101, v94
	v_add_f32_e32 v94, v102, v94
	v_pk_mul_f32 v[104:105], v[68:69], v[68:69]
	v_add_f32_e32 v94, v103, v94
	v_add_f32_e32 v94, v104, v94
	v_pk_mul_f32 v[106:107], v[70:71], v[70:71]
	v_add_f32_e32 v94, v105, v94
	v_add_f32_e32 v94, v106, v94
	v_pk_mul_f32 v[108:109], v[72:73], v[72:73]
	v_add_f32_e32 v94, v107, v94
	v_add_f32_e32 v94, v108, v94
	v_add_f32_e32 v94, v109, v94
	ds_bpermute_b32 v33, v33, v94
	s_waitcnt lgkmcnt(0)
	v_add_f32_e32 v33, v94, v33
	ds_bpermute_b32 v88, v88, v33
	s_waitcnt lgkmcnt(0)
	v_add_f32_e32 v33, v33, v88
	ds_bpermute_b32 v88, v90, v33
	s_waitcnt lgkmcnt(0)
	v_add_f32_e32 v33, v33, v88
	ds_bpermute_b32 v88, v91, v33
	s_waitcnt lgkmcnt(0)
	v_add_f32_e32 v33, v33, v88
	ds_bpermute_b32 v88, v92, v33
	s_waitcnt lgkmcnt(0)
	v_add_f32_e32 v33, v33, v88
	ds_bpermute_b32 v88, v93, v33
	s_waitcnt lgkmcnt(0)
	v_add_f32_e32 v33, v33, v88
	v_fmamk_f32 v33, v33, 0x3a800000, v205
	v_mul_f32_e32 v88, 0x4b800000, v33
	v_cmp_gt_f32_e32 vcc, s30, v33
	s_nop 1
	v_cndmask_b32_e32 v33, v33, v88, vcc
	v_rsq_f32_e32 v33, v33
	s_nop 0
	v_mul_f32_e32 v88, 0x45800000, v33
	v_cndmask_b32_e32 v88, v33, v88, vcc
.Lrp139_st_2:
	v_ashrrev_i32_e32 v33, 31, v32
	v_lshlrev_b64 v[32:33], 11, v[32:33]
	v_lshl_add_u64 v[90:91], v[48:49], 0, v[32:33]
	v_cvt_pk_bf16_f32 v92, v74, v75
	v_cvt_pk_bf16_f32 v93, v76, v77
	global_store_dwordx2 v[90:91], v[92:93], off
	v_cvt_pk_bf16_f32 v92, v78, v79
	v_cvt_pk_bf16_f32 v93, v80, v81
	global_store_dwordx2 v[90:91], v[92:93], off offset:512
	v_cvt_pk_bf16_f32 v92, v66, v67
	v_cvt_pk_bf16_f32 v93, v68, v69
	global_store_dwordx2 v[90:91], v[92:93], off offset:1024
	v_cvt_pk_bf16_f32 v92, v70, v71
	v_cvt_pk_bf16_f32 v93, v72, v73
	v_pk_mul_f32 v[74:75], v[74:75], v[88:89] op_sel_hi:[1,0]
	v_pk_mul_f32 v[76:77], v[76:77], v[88:89] op_sel_hi:[1,0]
	v_pk_mul_f32 v[78:79], v[78:79], v[88:89] op_sel_hi:[1,0]
	v_pk_mul_f32 v[80:81], v[80:81], v[88:89] op_sel_hi:[1,0]
	v_pk_mul_f32 v[66:67], v[66:67], v[88:89] op_sel_hi:[1,0]
	v_pk_mul_f32 v[68:69], v[68:69], v[88:89] op_sel_hi:[1,0]
	v_pk_mul_f32 v[70:71], v[70:71], v[88:89] op_sel_hi:[1,0]
	v_pk_mul_f32 v[72:73], v[72:73], v[88:89] op_sel_hi:[1,0]
	v_pk_mul_f32 v[74:75], v[16:17], v[74:75]
	v_pk_mul_f32 v[76:77], v[18:19], v[76:77]
	v_pk_mul_f32 v[78:79], v[20:21], v[78:79]
	v_pk_mul_f32 v[80:81], v[22:23], v[80:81]
	v_pk_mul_f32 v[66:67], v[24:25], v[66:67]
	v_pk_mul_f32 v[68:69], v[26:27], v[68:69]
	v_pk_mul_f32 v[70:71], v[28:29], v[70:71]
	v_pk_mul_f32 v[72:73], v[30:31], v[72:73]
	v_lshl_add_u64 v[32:33], v[58:59], 0, v[32:33]
	v_cvt_pk_bf16_f32 v74, v74, v75
	v_cvt_pk_bf16_f32 v75, v76, v77
	v_cvt_pk_bf16_f32 v78, v78, v79
	v_cvt_pk_bf16_f32 v79, v80, v81
	v_cvt_pk_bf16_f32 v66, v66, v67
	v_cvt_pk_bf16_f32 v67, v68, v69
	v_cvt_pk_bf16_f32 v70, v70, v71
	v_cvt_pk_bf16_f32 v71, v72, v73
	global_store_dwordx2 v[90:91], v[92:93], off offset:1536
	global_store_dwordx2 v[32:33], v[74:75], off
	global_store_dwordx2 v[32:33], v[78:79], off offset:512
	global_store_dwordx2 v[32:33], v[66:67], off offset:1024
	global_store_dwordx2 v[32:33], v[70:71], off offset:1536
	v_subrev_u32_e32 v32, s70, v89
	v_cmp_lt_i32_e32 vcc, s31, v32
	s_or_b64 s[8:9], vcc, s[8:9]
	s_andn2_b64 exec, exec, s[8:9]
	s_cbranch_execz .LBB0_141
	s_branch .LBB0_139

.LBB0_349:
	v_add_u32_e32 v33, s70, v32
	v_cmp_gt_i32_e32 vcc, s28, v33
	v_readlane_b32 s6, v254, 32
	v_readlane_b32 s7, v254, 33
	v_cndmask_b32_e32 v42, v32, v33, vcc
	v_ashrrev_i32_e32 v43, 31, v42
	v_lshlrev_b64 v[50:51], 11, v[42:43]
	v_lshl_add_u64 v[42:43], s[88:89], 0, v[50:51]
	v_lshl_add_u64 v[50:51], s[6:7], 0, v[50:51]
	v_lshl_add_u64 v[48:49], v[42:43], 0, v[188:189]
	v_lshl_add_u64 v[50:51], v[50:51], 0, v[188:189]
	global_load_dwordx2 v[42:43], v[48:49], off offset:1536
	global_load_dwordx2 v[44:45], v[48:49], off offset:1024
	global_load_dwordx2 v[46:47], v[48:49], off offset:512
	s_nop 0
	global_load_dwordx2 v[48:49], v[48:49], off
	s_nop 0
	global_load_dwordx2 v[54:55], v[50:51], off offset:1536
	global_load_dwordx2 v[58:59], v[50:51], off offset:1024
	global_load_dwordx2 v[60:61], v[50:51], off offset:512
	global_load_dwordx2 v[62:63], v[50:51], off
	v_lshl_add_u64 v[50:51], s[6:7], 0, v[188:189]
	v_readlane_b32 s6, v253, 2
	v_readlane_b32 s7, v253, 3
	v_lshl_add_u64 v[52:53], s[88:89], 0, v[188:189]
	v_mov_b32_e32 v86, v32
	v_lshl_add_u64 v[56:57], s[6:7], 0, v[188:189]
	s_mov_b64 s[6:7], 0
	s_waitcnt vmcnt(0)
	s_branch .LBB0_352
.LBB0_352:
	v_add_u32_e32 v33, s71, v86
	v_cmp_gt_i32_e32 vcc, s28, v33
	s_nop 1
	v_cndmask_b32_e32 v68, v86, v33, vcc
	v_ashrrev_i32_e32 v69, 31, v68
	v_lshlrev_b64 v[68:69], 11, v[68:69]
	v_lshl_add_u64 v[74:75], v[50:51], 0, v[68:69]
	v_lshl_add_u64 v[82:83], v[52:53], 0, v[68:69]
	global_load_dwordx2 v[68:69], v[74:75], off
	global_load_dwordx2 v[70:71], v[74:75], off offset:512
	global_load_dwordx2 v[72:73], v[74:75], off offset:1024
	s_nop 0
	global_load_dwordx2 v[74:75], v[74:75], off offset:1536
	s_nop 0
	global_load_dwordx2 v[76:77], v[82:83], off
	global_load_dwordx2 v[78:79], v[82:83], off offset:512
	s_waitcnt lgkmcnt(0)
	global_load_dwordx2 v[80:81], v[82:83], off offset:1024
	s_nop 0
	global_load_dwordx2 v[82:83], v[82:83], off offset:1536
	s_waitcnt vmcnt(32)
	v_lshlrev_b32_e32 v100, 16, v88
	v_and_b32_e32 v101, 0xffff0000, v88
	v_lshlrev_b32_e32 v98, 16, v89
	v_and_b32_e32 v99, 0xffff0000, v89
	v_pk_mul_f32 v[88:89], v[100:101], v[100:101]
	v_pk_mul_f32 v[94:95], v[98:99], v[98:99]
	v_add_f32_e32 v88, v88, v89
	v_lshlrev_b32_e32 v106, 16, v84
	v_and_b32_e32 v107, 0xffff0000, v84
	v_add_f32_e32 v88, v94, v88
	v_lshlrev_b32_e32 v102, 16, v85
	v_and_b32_e32 v103, 0xffff0000, v85
	v_pk_mul_f32 v[84:85], v[106:107], v[106:107]
	v_add_f32_e32 v88, v95, v88
	v_add_f32_e32 v84, v84, v88
	v_pk_mul_f32 v[104:105], v[102:103], v[102:103]
	v_add_f32_e32 v84, v85, v84
	v_lshlrev_b32_e32 v112, 16, v66
	v_and_b32_e32 v113, 0xffff0000, v66
	v_add_f32_e32 v84, v104, v84
	v_lshlrev_b32_e32 v108, 16, v67
	v_and_b32_e32 v109, 0xffff0000, v67
	v_pk_mul_f32 v[66:67], v[112:113], v[112:113]
	v_add_f32_e32 v84, v105, v84
	v_add_f32_e32 v66, v66, v84
	v_pk_mul_f32 v[110:111], v[108:109], v[108:109]
	v_add_f32_e32 v66, v67, v66
	v_lshlrev_b32_e32 v114, 16, v64
	v_and_b32_e32 v115, 0xffff0000, v64
	v_add_f32_e32 v66, v110, v66
	v_and_b32_e32 v87, 64, v207
	v_and_b32_e32 v97, 0xffff0000, v65
	v_lshlrev_b32_e32 v96, 16, v65
	v_pk_mul_f32 v[64:65], v[114:115], v[114:115]
	v_add_f32_e32 v66, v111, v66
	v_add_u32_e32 v116, 64, v87
	v_xor_b32_e32 v87, 32, v207
	v_add_f32_e32 v64, v64, v66
	v_cmp_lt_i32_e32 vcc, v87, v116
	v_pk_mul_f32 v[92:93], v[96:97], v[96:97]
	v_add_f32_e32 v64, v65, v64
	v_cndmask_b32_e32 v87, v207, v87, vcc
	v_add_f32_e32 v64, v92, v64
	v_lshlrev_b32_e32 v87, 2, v87
	v_add_f32_e32 v64, v93, v64
	ds_bpermute_b32 v65, v87, v64
	v_xor_b32_e32 v90, 16, v207
	v_cmp_lt_i32_e32 vcc, v90, v116
	v_xor_b32_e32 v91, 8, v207
	v_xor_b32_e32 v117, 4, v207
	v_cndmask_b32_e32 v90, v207, v90, vcc
	v_lshlrev_b32_e32 v90, 2, v90
	s_waitcnt lgkmcnt(0)
	v_add_f32_e32 v64, v64, v65
	ds_bpermute_b32 v65, v90, v64
	v_cmp_lt_i32_e32 vcc, v91, v116
	v_and_b32_e32 v105, 0xffff0000, v37
	v_lshlrev_b32_e32 v104, 16, v37
	v_cndmask_b32_e32 v91, v207, v91, vcc
	v_lshlrev_b32_e32 v91, 2, v91
	s_waitcnt lgkmcnt(0)
	v_add_f32_e32 v64, v64, v65
	ds_bpermute_b32 v65, v91, v64
	v_cmp_lt_i32_e32 vcc, v117, v116
	v_lshlrev_b32_e32 v110, 16, v38
	v_and_b32_e32 v111, 0xffff0000, v38
	v_cndmask_b32_e32 v66, v207, v117, vcc
	v_lshlrev_b32_e32 v92, 2, v66
	s_waitcnt lgkmcnt(0)
	v_add_f32_e32 v67, v64, v65
	ds_bpermute_b32 v84, v92, v67
	v_xor_b32_e32 v66, 2, v207
	v_cmp_lt_i32_e32 vcc, v66, v116
	v_lshlrev_b32_e32 v64, 16, v41
	v_and_b32_e32 v65, 0xffff0000, v41
	v_cndmask_b32_e32 v66, v207, v66, vcc
	v_lshlrev_b32_e32 v93, 2, v66
	s_waitcnt lgkmcnt(0)
	v_add_f32_e32 v37, v67, v84
	ds_bpermute_b32 v84, v93, v37
	v_xor_b32_e32 v66, 1, v207
	v_cmp_lt_i32_e32 vcc, v66, v116
	v_and_b32_e32 v67, 0xffff0000, v40
	v_and_b32_e32 v41, 0xffff0000, v39
	v_cndmask_b32_e32 v66, v207, v66, vcc
	v_lshlrev_b32_e32 v94, 2, v66
	s_waitcnt lgkmcnt(0)
	v_add_f32_e32 v37, v37, v84
	ds_bpermute_b32 v84, v94, v37
	v_lshlrev_b32_e32 v66, 16, v40
	v_lshlrev_b32_e32 v40, 16, v39
	v_lshlrev_b32_e32 v38, 16, v35
	v_and_b32_e32 v39, 0xffff0000, v35
	s_waitcnt lgkmcnt(0)
	v_add_f32_e32 v35, v37, v84
	v_fmamk_f32 v35, v35, 0x3a800000, v205
	v_mul_f32_e32 v37, 0x4b800000, v35
	v_cmp_gt_f32_e32 vcc, s30, v35
	v_lshlrev_b32_e32 v116, 16, v34
	v_and_b32_e32 v117, 0xffff0000, v34
	v_cndmask_b32_e32 v35, v35, v37, vcc
	v_rsq_f32_e32 v37, v35
	v_lshlrev_b32_e32 v34, 16, v36
	v_and_b32_e32 v35, 0xffff0000, v36
	v_mul_f32_e32 v36, 0x45800000, v37
	v_cndmask_b32_e32 v36, v37, v36, vcc
	v_pk_mul_f32 v[84:85], v[36:37], v[100:101] op_sel_hi:[0,1]
	v_pk_fma_f32 v[88:89], v[0:1], v[84:85], v[66:67]
	v_pk_mul_f32 v[66:67], v[36:37], v[98:99] op_sel_hi:[0,1]
	v_pk_fma_f32 v[84:85], v[2:3], v[66:67], v[64:65]
	v_pk_mul_f32 v[64:65], v[36:37], v[106:107] op_sel_hi:[0,1]
	v_pk_fma_f32 v[66:67], v[4:5], v[64:65], v[110:111]
	v_pk_mul_f32 v[64:65], v[36:37], v[102:103] op_sel_hi:[0,1]
	v_pk_mul_f32 v[98:99], v[36:37], v[108:109] op_sel_hi:[0,1]
	v_pk_fma_f32 v[64:65], v[6:7], v[64:65], v[40:41]
	v_pk_mul_f32 v[40:41], v[36:37], v[112:113] op_sel_hi:[0,1]
	v_pk_fma_f32 v[38:39], v[10:11], v[98:99], v[38:39]
	v_pk_mul_f32 v[98:99], v[36:37], v[114:115] op_sel_hi:[0,1]
	v_pk_mul_f32 v[36:37], v[36:37], v[96:97] op_sel_hi:[0,1]
	v_pk_fma_f32 v[40:41], v[8:9], v[40:41], v[116:117]
	v_pk_fma_f32 v[34:35], v[12:13], v[98:99], v[34:35]
	s_and_b64 vcc, exec, s[4:5]
	v_pk_fma_f32 v[36:37], v[14:15], v[36:37], v[104:105]
	s_cbranch_vccz .Lrp352_n2_0
	v_mov_b32_e32 v90, 1.0
	s_branch .Lrp352_st_0

.Lrp352_st_0:
	v_ashrrev_i32_e32 v87, 31, v86
	v_lshlrev_b64 v[86:87], 11, v[86:87]
	v_lshl_add_u64 v[92:93], v[56:57], 0, v[86:87]
	v_cvt_pk_bf16_f32 v94, v88, v89
	v_cvt_pk_bf16_f32 v95, v84, v85
	global_store_dwordx2 v[92:93], v[94:95], off
	v_cvt_pk_bf16_f32 v94, v66, v67
	v_cvt_pk_bf16_f32 v95, v64, v65
	global_store_dwordx2 v[92:93], v[94:95], off offset:512
	v_cvt_pk_bf16_f32 v94, v40, v41
	v_cvt_pk_bf16_f32 v95, v38, v39
	global_store_dwordx2 v[92:93], v[94:95], off offset:1024
	v_cvt_pk_bf16_f32 v94, v34, v35
	v_cvt_pk_bf16_f32 v95, v36, v37
	v_pk_mul_f32 v[88:89], v[88:89], v[90:91] op_sel_hi:[1,0]
	v_pk_mul_f32 v[84:85], v[84:85], v[90:91] op_sel_hi:[1,0]
	v_pk_mul_f32 v[66:67], v[66:67], v[90:91] op_sel_hi:[1,0]
	v_pk_mul_f32 v[64:65], v[64:65], v[90:91] op_sel_hi:[1,0]
	v_pk_mul_f32 v[40:41], v[40:41], v[90:91] op_sel_hi:[1,0]
	v_pk_mul_f32 v[38:39], v[38:39], v[90:91] op_sel_hi:[1,0]
	v_pk_mul_f32 v[34:35], v[34:35], v[90:91] op_sel_hi:[1,0]
	v_pk_mul_f32 v[36:37], v[36:37], v[90:91] op_sel_hi:[1,0]
	v_pk_mul_f32 v[88:89], v[16:17], v[88:89]
	v_pk_mul_f32 v[84:85], v[18:19], v[84:85]
	v_pk_mul_f32 v[66:67], v[20:21], v[66:67]
	v_pk_mul_f32 v[64:65], v[22:23], v[64:65]
	v_pk_mul_f32 v[40:41], v[24:25], v[40:41]
	v_pk_mul_f32 v[38:39], v[26:27], v[38:39]
	v_pk_mul_f32 v[34:35], v[28:29], v[34:35]
	v_pk_mul_f32 v[36:37], v[30:31], v[36:37]
	v_lshl_add_u64 v[86:87], v[50:51], 0, v[86:87]
	v_cvt_pk_bf16_f32 v88, v88, v89
	v_cvt_pk_bf16_f32 v89, v84, v85
	v_cvt_pk_bf16_f32 v66, v66, v67
	v_cvt_pk_bf16_f32 v67, v64, v65
	v_cvt_pk_bf16_f32 v40, v40, v41
	v_cvt_pk_bf16_f32 v41, v38, v39
	v_cvt_pk_bf16_f32 v34, v34, v35
	v_cvt_pk_bf16_f32 v35, v36, v37
	global_store_dwordx2 v[92:93], v[94:95], off offset:1536
	global_store_dwordx2 v[86:87], v[88:89], off
	global_store_dwordx2 v[86:87], v[66:67], off offset:512
	global_store_dwordx2 v[86:87], v[40:41], off offset:1024
	global_store_dwordx2 v[86:87], v[34:35], off offset:1536
	v_subrev_u32_e32 v86, s70, v33
	v_cmp_lt_i32_e32 vcc, s31, v86
	s_or_b64 s[6:7], vcc, s[6:7]
	s_andn2_b64 exec, exec, s[6:7]
	s_cbranch_execz .LBB0_354
.Lrp352_top1:
	v_add_u32_e32 v33, s71, v86
	v_cmp_gt_i32_e32 vcc, s28, v33
	s_nop 1
	v_cndmask_b32_e32 v40, v86, v33, vcc
	v_ashrrev_i32_e32 v41, 31, v40
	v_lshlrev_b64 v[40:41], 11, v[40:41]
	v_lshl_add_u64 v[36:37], v[50:51], 0, v[40:41]
	v_lshl_add_u64 v[64:65], v[52:53], 0, v[40:41]
	global_load_dwordx2 v[40:41], v[36:37], off
	global_load_dwordx2 v[38:39], v[36:37], off offset:512
	global_load_dwordx2 v[34:35], v[36:37], off offset:1024
	s_nop 0
	global_load_dwordx2 v[36:37], v[36:37], off offset:1536
	s_nop 0
	global_load_dwordx2 v[88:89], v[64:65], off
	global_load_dwordx2 v[84:85], v[64:65], off offset:512
	s_waitcnt lgkmcnt(0)
	global_load_dwordx2 v[66:67], v[64:65], off offset:1024
	s_nop 0
	global_load_dwordx2 v[64:65], v[64:65], off offset:1536
	s_waitcnt vmcnt(32)
	v_lshlrev_b32_e32 v100, 16, v48
	v_and_b32_e32 v101, 0xffff0000, v48
	v_lshlrev_b32_e32 v98, 16, v49
	v_and_b32_e32 v99, 0xffff0000, v49
	v_pk_mul_f32 v[48:49], v[100:101], v[100:101]
	v_pk_mul_f32 v[94:95], v[98:99], v[98:99]
	v_add_f32_e32 v48, v48, v49
	v_lshlrev_b32_e32 v106, 16, v46
	v_and_b32_e32 v107, 0xffff0000, v46
	v_add_f32_e32 v48, v94, v48
	v_lshlrev_b32_e32 v102, 16, v47
	v_and_b32_e32 v103, 0xffff0000, v47
	v_pk_mul_f32 v[46:47], v[106:107], v[106:107]
	v_add_f32_e32 v48, v95, v48
	v_add_f32_e32 v46, v46, v48
	v_pk_mul_f32 v[104:105], v[102:103], v[102:103]
	v_add_f32_e32 v46, v47, v46
	v_lshlrev_b32_e32 v112, 16, v44
	v_and_b32_e32 v113, 0xffff0000, v44
	v_add_f32_e32 v46, v104, v46
	v_lshlrev_b32_e32 v108, 16, v45
	v_and_b32_e32 v109, 0xffff0000, v45
	v_pk_mul_f32 v[44:45], v[112:113], v[112:113]
	v_add_f32_e32 v46, v105, v46
	v_add_f32_e32 v44, v44, v46
	v_pk_mul_f32 v[110:111], v[108:109], v[108:109]
	v_add_f32_e32 v44, v45, v44
	v_lshlrev_b32_e32 v114, 16, v42
	v_and_b32_e32 v115, 0xffff0000, v42
	v_add_f32_e32 v44, v110, v44
	v_and_b32_e32 v87, 64, v207
	v_and_b32_e32 v97, 0xffff0000, v43
	v_lshlrev_b32_e32 v96, 16, v43
	v_pk_mul_f32 v[42:43], v[114:115], v[114:115]
	v_add_f32_e32 v44, v111, v44
	v_add_u32_e32 v116, 64, v87
	v_xor_b32_e32 v87, 32, v207
	v_add_f32_e32 v42, v42, v44
	v_cmp_lt_i32_e32 vcc, v87, v116
	v_pk_mul_f32 v[92:93], v[96:97], v[96:97]
	v_add_f32_e32 v42, v43, v42
	v_cndmask_b32_e32 v87, v207, v87, vcc
	v_add_f32_e32 v42, v92, v42
	v_lshlrev_b32_e32 v87, 2, v87
	v_add_f32_e32 v42, v93, v42
	ds_bpermute_b32 v43, v87, v42
	v_xor_b32_e32 v90, 16, v207
	v_cmp_lt_i32_e32 vcc, v90, v116
	v_xor_b32_e32 v91, 8, v207
	v_xor_b32_e32 v117, 4, v207
	v_cndmask_b32_e32 v90, v207, v90, vcc
	v_lshlrev_b32_e32 v90, 2, v90
	s_waitcnt lgkmcnt(0)
	v_add_f32_e32 v42, v42, v43
	ds_bpermute_b32 v43, v90, v42
	v_cmp_lt_i32_e32 vcc, v91, v116
	v_and_b32_e32 v105, 0xffff0000, v55
	v_lshlrev_b32_e32 v104, 16, v55
	v_cndmask_b32_e32 v91, v207, v91, vcc
	v_lshlrev_b32_e32 v91, 2, v91
	s_waitcnt lgkmcnt(0)
	v_add_f32_e32 v42, v42, v43
	ds_bpermute_b32 v43, v91, v42
	v_cmp_lt_i32_e32 vcc, v117, v116
	v_lshlrev_b32_e32 v110, 16, v60
	v_and_b32_e32 v111, 0xffff0000, v60
	v_cndmask_b32_e32 v44, v207, v117, vcc
	v_lshlrev_b32_e32 v92, 2, v44
	s_waitcnt lgkmcnt(0)
	v_add_f32_e32 v45, v42, v43
	ds_bpermute_b32 v46, v92, v45
	v_xor_b32_e32 v44, 2, v207
	v_cmp_lt_i32_e32 vcc, v44, v116
	v_lshlrev_b32_e32 v42, 16, v63
	v_and_b32_e32 v43, 0xffff0000, v63
	v_cndmask_b32_e32 v44, v207, v44, vcc
	v_lshlrev_b32_e32 v93, 2, v44
	s_waitcnt lgkmcnt(0)
	v_add_f32_e32 v55, v45, v46
	ds_bpermute_b32 v46, v93, v55
	v_xor_b32_e32 v44, 1, v207
	v_cmp_lt_i32_e32 vcc, v44, v116
	v_and_b32_e32 v45, 0xffff0000, v62
	v_and_b32_e32 v63, 0xffff0000, v61
	v_cndmask_b32_e32 v44, v207, v44, vcc
	v_lshlrev_b32_e32 v94, 2, v44
	s_waitcnt lgkmcnt(0)
	v_add_f32_e32 v55, v55, v46
	ds_bpermute_b32 v46, v94, v55
	v_lshlrev_b32_e32 v44, 16, v62
	v_lshlrev_b32_e32 v62, 16, v61
	v_lshlrev_b32_e32 v60, 16, v59
	v_and_b32_e32 v61, 0xffff0000, v59
	s_waitcnt lgkmcnt(0)
	v_add_f32_e32 v59, v55, v46
	v_fmamk_f32 v59, v59, 0x3a800000, v205
	v_mul_f32_e32 v55, 0x4b800000, v59
	v_cmp_gt_f32_e32 vcc, s30, v59
	v_lshlrev_b32_e32 v116, 16, v58
	v_and_b32_e32 v117, 0xffff0000, v58
	v_cndmask_b32_e32 v59, v59, v55, vcc
	v_rsq_f32_e32 v55, v59
	v_lshlrev_b32_e32 v58, 16, v54
	v_and_b32_e32 v59, 0xffff0000, v54
	v_mul_f32_e32 v54, 0x45800000, v55
	v_cndmask_b32_e32 v54, v55, v54, vcc
	v_pk_mul_f32 v[46:47], v[54:55], v[100:101] op_sel_hi:[0,1]
	v_pk_fma_f32 v[48:49], v[0:1], v[46:47], v[44:45]
	v_pk_mul_f32 v[44:45], v[54:55], v[98:99] op_sel_hi:[0,1]
	v_pk_fma_f32 v[46:47], v[2:3], v[44:45], v[42:43]
	v_pk_mul_f32 v[42:43], v[54:55], v[106:107] op_sel_hi:[0,1]
	v_pk_fma_f32 v[44:45], v[4:5], v[42:43], v[110:111]
	v_pk_mul_f32 v[42:43], v[54:55], v[102:103] op_sel_hi:[0,1]
	v_pk_mul_f32 v[98:99], v[54:55], v[108:109] op_sel_hi:[0,1]
	v_pk_fma_f32 v[42:43], v[6:7], v[42:43], v[62:63]
	v_pk_mul_f32 v[62:63], v[54:55], v[112:113] op_sel_hi:[0,1]
	v_pk_fma_f32 v[60:61], v[10:11], v[98:99], v[60:61]
	v_pk_mul_f32 v[98:99], v[54:55], v[114:115] op_sel_hi:[0,1]
	v_pk_mul_f32 v[54:55], v[54:55], v[96:97] op_sel_hi:[0,1]
	v_pk_fma_f32 v[62:63], v[8:9], v[62:63], v[116:117]
	v_pk_fma_f32 v[58:59], v[12:13], v[98:99], v[58:59]
	s_and_b64 vcc, exec, s[4:5]
	v_pk_fma_f32 v[54:55], v[14:15], v[54:55], v[104:105]
	s_cbranch_vccz .Lrp352_n2_1
	v_mov_b32_e32 v90, 1.0
	s_branch .Lrp352_st_1
.Lrp352_n2_1:
	v_pk_mul_f32 v[96:97], v[48:49], v[48:49]
	v_pk_mul_f32 v[98:99], v[46:47], v[46:47]
	v_add_f32_e32 v95, v96, v97
	v_add_f32_e32 v95, v98, v95
	v_pk_mul_f32 v[100:101], v[44:45], v[44:45]
	v_add_f32_e32 v95, v99, v95
	v_add_f32_e32 v95, v100, v95
	v_pk_mul_f32 v[102:103], v[42:43], v[42:43]
	v_add_f32_e32 v95, v101, v95
	v_add_f32_e32 v95, v102, v95
	v_pk_mul_f32 v[104:105], v[62:63], v[62:63]
	v_add_f32_e32 v95, v103, v95
	v_add_f32_e32 v95, v104, v95
	v_pk_mul_f32 v[106:107], v[60:61], v[60:61]
	v_add_f32_e32 v95, v105, v95
	v_add_f32_e32 v95, v106, v95
	v_pk_mul_f32 v[108:109], v[58:59], v[58:59]
	v_add_f32_e32 v95, v107, v95
	v_add_f32_e32 v95, v108, v95
	v_pk_mul_f32 v[110:111], v[54:55], v[54:55]
	v_add_f32_e32 v95, v109, v95
	v_add_f32_e32 v95, v110, v95
	v_add_f32_e32 v95, v111, v95
	ds_bpermute_b32 v87, v87, v95
	s_waitcnt lgkmcnt(0)
	v_add_f32_e32 v87, v95, v87
	ds_bpermute_b32 v90, v90, v87
	s_waitcnt lgkmcnt(0)
	v_add_f32_e32 v87, v87, v90
	ds_bpermute_b32 v90, v91, v87
	s_waitcnt lgkmcnt(0)
	v_add_f32_e32 v87, v87, v90
	ds_bpermute_b32 v90, v92, v87
	s_waitcnt lgkmcnt(0)
	v_add_f32_e32 v87, v87, v90
	ds_bpermute_b32 v90, v93, v87
	s_waitcnt lgkmcnt(0)
	v_add_f32_e32 v87, v87, v90
	ds_bpermute_b32 v90, v94, v87
	s_waitcnt lgkmcnt(0)
	v_add_f32_e32 v87, v87, v90
	v_fmamk_f32 v87, v87, 0x3a800000, v205
	v_mul_f32_e32 v90, 0x4b800000, v87
	v_cmp_gt_f32_e32 vcc, s30, v87
	s_nop 1
	v_cndmask_b32_e32 v87, v87, v90, vcc
	v_rsq_f32_e32 v87, v87
	s_nop 0
	v_mul_f32_e32 v90, 0x45800000, v87
	v_cndmask_b32_e32 v90, v87, v90, vcc
.Lrp352_st_1:
	v_ashrrev_i32_e32 v87, 31, v86
	v_lshlrev_b64 v[86:87], 11, v[86:87]
	v_lshl_add_u64 v[92:93], v[56:57], 0, v[86:87]
	v_cvt_pk_bf16_f32 v94, v48, v49
	v_cvt_pk_bf16_f32 v95, v46, v47
	global_store_dwordx2 v[92:93], v[94:95], off
	v_cvt_pk_bf16_f32 v94, v44, v45
	v_cvt_pk_bf16_f32 v95, v42, v43
	global_store_dwordx2 v[92:93], v[94:95], off offset:512
	v_cvt_pk_bf16_f32 v94, v62, v63
	v_cvt_pk_bf16_f32 v95, v60, v61
	global_store_dwordx2 v[92:93], v[94:95], off offset:1024
	v_cvt_pk_bf16_f32 v94, v58, v59
	v_cvt_pk_bf16_f32 v95, v54, v55
	v_pk_mul_f32 v[48:49], v[48:49], v[90:91] op_sel_hi:[1,0]
	v_pk_mul_f32 v[46:47], v[46:47], v[90:91] op_sel_hi:[1,0]
	v_pk_mul_f32 v[44:45], v[44:45], v[90:91] op_sel_hi:[1,0]
	v_pk_mul_f32 v[42:43], v[42:43], v[90:91] op_sel_hi:[1,0]
	v_pk_mul_f32 v[62:63], v[62:63], v[90:91] op_sel_hi:[1,0]
	v_pk_mul_f32 v[60:61], v[60:61], v[90:91] op_sel_hi:[1,0]
	v_pk_mul_f32 v[58:59], v[58:59], v[90:91] op_sel_hi:[1,0]
	v_pk_mul_f32 v[54:55], v[54:55], v[90:91] op_sel_hi:[1,0]
	v_pk_mul_f32 v[48:49], v[16:17], v[48:49]
	v_pk_mul_f32 v[46:47], v[18:19], v[46:47]
	v_pk_mul_f32 v[44:45], v[20:21], v[44:45]
	v_pk_mul_f32 v[42:43], v[22:23], v[42:43]
	v_pk_mul_f32 v[62:63], v[24:25], v[62:63]
	v_pk_mul_f32 v[60:61], v[26:27], v[60:61]
	v_pk_mul_f32 v[58:59], v[28:29], v[58:59]
	v_pk_mul_f32 v[54:55], v[30:31], v[54:55]
	v_lshl_add_u64 v[86:87], v[50:51], 0, v[86:87]
	v_cvt_pk_bf16_f32 v48, v48, v49
	v_cvt_pk_bf16_f32 v49, v46, v47
	v_cvt_pk_bf16_f32 v44, v44, v45
	v_cvt_pk_bf16_f32 v45, v42, v43
	v_cvt_pk_bf16_f32 v62, v62, v63
	v_cvt_pk_bf16_f32 v63, v60, v61
	v_cvt_pk_bf16_f32 v58, v58, v59
	v_cvt_pk_bf16_f32 v59, v54, v55
	global_store_dwordx2 v[92:93], v[94:95], off offset:1536
	global_store_dwordx2 v[86:87], v[48:49], off
	global_store_dwordx2 v[86:87], v[44:45], off offset:512
	global_store_dwordx2 v[86:87], v[62:63], off offset:1024
	global_store_dwordx2 v[86:87], v[58:59], off offset:1536
	v_subrev_u32_e32 v86, s70, v33
	v_cmp_lt_i32_e32 vcc, s31, v86
	s_or_b64 s[6:7], vcc, s[6:7]
	s_andn2_b64 exec, exec, s[6:7]
	s_cbranch_execz .LBB0_354
.Lrp352_top2:
	v_add_u32_e32 v33, s71, v86
	v_cmp_gt_i32_e32 vcc, s28, v33
	s_nop 1
	v_cndmask_b32_e32 v62, v86, v33, vcc
	v_ashrrev_i32_e32 v63, 31, v62
	v_lshlrev_b64 v[62:63], 11, v[62:63]
	v_lshl_add_u64 v[54:55], v[50:51], 0, v[62:63]
	v_lshl_add_u64 v[42:43], v[52:53], 0, v[62:63]
	global_load_dwordx2 v[62:63], v[54:55], off
	global_load_dwordx2 v[60:61], v[54:55], off offset:512
	global_load_dwordx2 v[58:59], v[54:55], off offset:1024
	s_nop 0
	global_load_dwordx2 v[54:55], v[54:55], off offset:1536
	s_nop 0
	global_load_dwordx2 v[48:49], v[42:43], off
	global_load_dwordx2 v[46:47], v[42:43], off offset:512
	s_waitcnt lgkmcnt(0)
	global_load_dwordx2 v[44:45], v[42:43], off offset:1024
	s_nop 0
	global_load_dwordx2 v[42:43], v[42:43], off offset:1536
	s_waitcnt vmcnt(32)
	v_lshlrev_b32_e32 v100, 16, v76
	v_and_b32_e32 v101, 0xffff0000, v76
	v_lshlrev_b32_e32 v98, 16, v77
	v_and_b32_e32 v99, 0xffff0000, v77
	v_pk_mul_f32 v[76:77], v[100:101], v[100:101]
	v_pk_mul_f32 v[94:95], v[98:99], v[98:99]
	v_add_f32_e32 v76, v76, v77
	v_lshlrev_b32_e32 v106, 16, v78
	v_and_b32_e32 v107, 0xffff0000, v78
	v_add_f32_e32 v76, v94, v76
	v_lshlrev_b32_e32 v102, 16, v79
	v_and_b32_e32 v103, 0xffff0000, v79
	v_pk_mul_f32 v[78:79], v[106:107], v[106:107]
	v_add_f32_e32 v76, v95, v76
	v_add_f32_e32 v78, v78, v76
	v_pk_mul_f32 v[104:105], v[102:103], v[102:103]
	v_add_f32_e32 v78, v79, v78
	v_lshlrev_b32_e32 v112, 16, v80
	v_and_b32_e32 v113, 0xffff0000, v80
	v_add_f32_e32 v78, v104, v78
	v_lshlrev_b32_e32 v108, 16, v81
	v_and_b32_e32 v109, 0xffff0000, v81
	v_pk_mul_f32 v[80:81], v[112:113], v[112:113]
	v_add_f32_e32 v78, v105, v78
	v_add_f32_e32 v80, v80, v78
	v_pk_mul_f32 v[110:111], v[108:109], v[108:109]
	v_add_f32_e32 v80, v81, v80
	v_lshlrev_b32_e32 v114, 16, v82
	v_and_b32_e32 v115, 0xffff0000, v82
	v_add_f32_e32 v80, v110, v80
	v_and_b32_e32 v87, 64, v207
	v_and_b32_e32 v97, 0xffff0000, v83
	v_lshlrev_b32_e32 v96, 16, v83
	v_pk_mul_f32 v[82:83], v[114:115], v[114:115]
	v_add_f32_e32 v80, v111, v80
	v_add_u32_e32 v116, 64, v87
	v_xor_b32_e32 v87, 32, v207
	v_add_f32_e32 v82, v82, v80
	v_cmp_lt_i32_e32 vcc, v87, v116
	v_pk_mul_f32 v[92:93], v[96:97], v[96:97]
	v_add_f32_e32 v82, v83, v82
	v_cndmask_b32_e32 v87, v207, v87, vcc
	v_add_f32_e32 v82, v92, v82
	v_lshlrev_b32_e32 v87, 2, v87
	v_add_f32_e32 v82, v93, v82
	ds_bpermute_b32 v83, v87, v82
	v_xor_b32_e32 v90, 16, v207
	v_cmp_lt_i32_e32 vcc, v90, v116
	v_xor_b32_e32 v91, 8, v207
	v_xor_b32_e32 v117, 4, v207
	v_cndmask_b32_e32 v90, v207, v90, vcc
	v_lshlrev_b32_e32 v90, 2, v90
	s_waitcnt lgkmcnt(0)
	v_add_f32_e32 v82, v82, v83
	ds_bpermute_b32 v83, v90, v82
	v_cmp_lt_i32_e32 vcc, v91, v116
	v_and_b32_e32 v105, 0xffff0000, v75
	v_lshlrev_b32_e32 v104, 16, v75
	v_cndmask_b32_e32 v91, v207, v91, vcc
	v_lshlrev_b32_e32 v91, 2, v91
	s_waitcnt lgkmcnt(0)
	v_add_f32_e32 v82, v82, v83
	ds_bpermute_b32 v83, v91, v82
	v_cmp_lt_i32_e32 vcc, v117, v116
	v_lshlrev_b32_e32 v110, 16, v70
	v_and_b32_e32 v111, 0xffff0000, v70
	v_cndmask_b32_e32 v80, v207, v117, vcc
	v_lshlrev_b32_e32 v92, 2, v80
	s_waitcnt lgkmcnt(0)
	v_add_f32_e32 v81, v82, v83
	ds_bpermute_b32 v78, v92, v81
	v_xor_b32_e32 v80, 2, v207
	v_cmp_lt_i32_e32 vcc, v80, v116
	v_lshlrev_b32_e32 v82, 16, v69
	v_and_b32_e32 v83, 0xffff0000, v69
	v_cndmask_b32_e32 v80, v207, v80, vcc
	v_lshlrev_b32_e32 v93, 2, v80
	s_waitcnt lgkmcnt(0)
	v_add_f32_e32 v75, v81, v78
	ds_bpermute_b32 v78, v93, v75
	v_xor_b32_e32 v80, 1, v207
	v_cmp_lt_i32_e32 vcc, v80, v116
	v_and_b32_e32 v81, 0xffff0000, v68
	v_and_b32_e32 v69, 0xffff0000, v71
	v_cndmask_b32_e32 v80, v207, v80, vcc
	v_lshlrev_b32_e32 v94, 2, v80
	s_waitcnt lgkmcnt(0)
	v_add_f32_e32 v75, v75, v78
	ds_bpermute_b32 v78, v94, v75
	v_lshlrev_b32_e32 v80, 16, v68
	v_lshlrev_b32_e32 v68, 16, v71
	v_lshlrev_b32_e32 v70, 16, v73
	v_and_b32_e32 v71, 0xffff0000, v73
	s_waitcnt lgkmcnt(0)
	v_add_f32_e32 v73, v75, v78
	v_fmamk_f32 v73, v73, 0x3a800000, v205
	v_mul_f32_e32 v75, 0x4b800000, v73
	v_cmp_gt_f32_e32 vcc, s30, v73
	v_lshlrev_b32_e32 v116, 16, v72
	v_and_b32_e32 v117, 0xffff0000, v72
	v_cndmask_b32_e32 v73, v73, v75, vcc
	v_rsq_f32_e32 v75, v73
	v_lshlrev_b32_e32 v72, 16, v74
	v_and_b32_e32 v73, 0xffff0000, v74
	v_mul_f32_e32 v74, 0x45800000, v75
	v_cndmask_b32_e32 v74, v75, v74, vcc
	v_pk_mul_f32 v[78:79], v[74:75], v[100:101] op_sel_hi:[0,1]
	v_pk_fma_f32 v[76:77], v[0:1], v[78:79], v[80:81]
	v_pk_mul_f32 v[80:81], v[74:75], v[98:99] op_sel_hi:[0,1]
	v_pk_fma_f32 v[78:79], v[2:3], v[80:81], v[82:83]
	v_pk_mul_f32 v[82:83], v[74:75], v[106:107] op_sel_hi:[0,1]
	v_pk_fma_f32 v[80:81], v[4:5], v[82:83], v[110:111]
	v_pk_mul_f32 v[82:83], v[74:75], v[102:103] op_sel_hi:[0,1]
	v_pk_mul_f32 v[98:99], v[74:75], v[108:109] op_sel_hi:[0,1]
	v_pk_fma_f32 v[82:83], v[6:7], v[82:83], v[68:69]
	v_pk_mul_f32 v[68:69], v[74:75], v[112:113] op_sel_hi:[0,1]
	v_pk_fma_f32 v[70:71], v[10:11], v[98:99], v[70:71]
	v_pk_mul_f32 v[98:99], v[74:75], v[114:115] op_sel_hi:[0,1]
	v_pk_mul_f32 v[74:75], v[74:75], v[96:97] op_sel_hi:[0,1]
	v_pk_fma_f32 v[68:69], v[8:9], v[68:69], v[116:117]
	v_pk_fma_f32 v[72:73], v[12:13], v[98:99], v[72:73]
	s_and_b64 vcc, exec, s[4:5]
	v_pk_fma_f32 v[74:75], v[14:15], v[74:75], v[104:105]
	s_cbranch_vccz .Lrp352_n2_2
	v_mov_b32_e32 v90, 1.0
	s_branch .Lrp352_st_2
.Lrp352_n2_2:
	v_pk_mul_f32 v[96:97], v[76:77], v[76:77]
	v_pk_mul_f32 v[98:99], v[78:79], v[78:79]
	v_add_f32_e32 v95, v96, v97
	v_add_f32_e32 v95, v98, v95
	v_pk_mul_f32 v[100:101], v[80:81], v[80:81]
	v_add_f32_e32 v95, v99, v95
	v_add_f32_e32 v95, v100, v95
	v_pk_mul_f32 v[102:103], v[82:83], v[82:83]
	v_add_f32_e32 v95, v101, v95
	v_add_f32_e32 v95, v102, v95
	v_pk_mul_f32 v[104:105], v[68:69], v[68:69]
	v_add_f32_e32 v95, v103, v95
	v_add_f32_e32 v95, v104, v95
	v_pk_mul_f32 v[106:107], v[70:71], v[70:71]
	v_add_f32_e32 v95, v105, v95
	v_add_f32_e32 v95, v106, v95
	v_pk_mul_f32 v[108:109], v[72:73], v[72:73]
	v_add_f32_e32 v95, v107, v95
	v_add_f32_e32 v95, v108, v95
	v_pk_mul_f32 v[110:111], v[74:75], v[74:75]
	v_add_f32_e32 v95, v109, v95
	v_add_f32_e32 v95, v110, v95
	v_add_f32_e32 v95, v111, v95
	ds_bpermute_b32 v87, v87, v95
	s_waitcnt lgkmcnt(0)
	v_add_f32_e32 v87, v95, v87
	ds_bpermute_b32 v90, v90, v87
	s_waitcnt lgkmcnt(0)
	v_add_f32_e32 v87, v87, v90
	ds_bpermute_b32 v90, v91, v87
	s_waitcnt lgkmcnt(0)
	v_add_f32_e32 v87, v87, v90
	ds_bpermute_b32 v90, v92, v87
	s_waitcnt lgkmcnt(0)
	v_add_f32_e32 v87, v87, v90
	ds_bpermute_b32 v90, v93, v87
	s_waitcnt lgkmcnt(0)
	v_add_f32_e32 v87, v87, v90
	ds_bpermute_b32 v90, v94, v87
	s_waitcnt lgkmcnt(0)
	v_add_f32_e32 v87, v87, v90
	v_fmamk_f32 v87, v87, 0x3a800000, v205
	v_mul_f32_e32 v90, 0x4b800000, v87
	v_cmp_gt_f32_e32 vcc, s30, v87
	s_nop 1
	v_cndmask_b32_e32 v87, v87, v90, vcc
	v_rsq_f32_e32 v87, v87
	s_nop 0
	v_mul_f32_e32 v90, 0x45800000, v87
	v_cndmask_b32_e32 v90, v87, v90, vcc
.Lrp352_st_2:
	v_ashrrev_i32_e32 v87, 31, v86
	v_lshlrev_b64 v[86:87], 11, v[86:87]
	v_lshl_add_u64 v[92:93], v[56:57], 0, v[86:87]
	v_cvt_pk_bf16_f32 v94, v76, v77
	v_cvt_pk_bf16_f32 v95, v78, v79
	global_store_dwordx2 v[92:93], v[94:95], off
	v_cvt_pk_bf16_f32 v94, v80, v81
	v_cvt_pk_bf16_f32 v95, v82, v83
	global_store_dwordx2 v[92:93], v[94:95], off offset:512
	v_cvt_pk_bf16_f32 v94, v68, v69
	v_cvt_pk_bf16_f32 v95, v70, v71
	global_store_dwordx2 v[92:93], v[94:95], off offset:1024
	v_cvt_pk_bf16_f32 v94, v72, v73
	v_cvt_pk_bf16_f32 v95, v74, v75
	v_pk_mul_f32 v[76:77], v[76:77], v[90:91] op_sel_hi:[1,0]
	v_pk_mul_f32 v[78:79], v[78:79], v[90:91] op_sel_hi:[1,0]
	v_pk_mul_f32 v[80:81], v[80:81], v[90:91] op_sel_hi:[1,0]
	v_pk_mul_f32 v[82:83], v[82:83], v[90:91] op_sel_hi:[1,0]
	v_pk_mul_f32 v[68:69], v[68:69], v[90:91] op_sel_hi:[1,0]
	v_pk_mul_f32 v[70:71], v[70:71], v[90:91] op_sel_hi:[1,0]
	v_pk_mul_f32 v[72:73], v[72:73], v[90:91] op_sel_hi:[1,0]
	v_pk_mul_f32 v[74:75], v[74:75], v[90:91] op_sel_hi:[1,0]
	v_pk_mul_f32 v[76:77], v[16:17], v[76:77]
	v_pk_mul_f32 v[78:79], v[18:19], v[78:79]
	v_pk_mul_f32 v[80:81], v[20:21], v[80:81]
	v_pk_mul_f32 v[82:83], v[22:23], v[82:83]
	v_pk_mul_f32 v[68:69], v[24:25], v[68:69]
	v_pk_mul_f32 v[70:71], v[26:27], v[70:71]
	v_pk_mul_f32 v[72:73], v[28:29], v[72:73]
	v_pk_mul_f32 v[74:75], v[30:31], v[74:75]
	v_lshl_add_u64 v[86:87], v[50:51], 0, v[86:87]
	v_cvt_pk_bf16_f32 v76, v76, v77
	v_cvt_pk_bf16_f32 v77, v78, v79
	v_cvt_pk_bf16_f32 v80, v80, v81
	v_cvt_pk_bf16_f32 v81, v82, v83
	v_cvt_pk_bf16_f32 v68, v68, v69
	v_cvt_pk_bf16_f32 v69, v70, v71
	v_cvt_pk_bf16_f32 v72, v72, v73
	v_cvt_pk_bf16_f32 v73, v74, v75
	global_store_dwordx2 v[92:93], v[94:95], off offset:1536
	global_store_dwordx2 v[86:87], v[76:77], off
	global_store_dwordx2 v[86:87], v[80:81], off offset:512
	global_store_dwordx2 v[86:87], v[68:69], off offset:1024
	global_store_dwordx2 v[86:87], v[72:73], off offset:1536
	v_subrev_u32_e32 v86, s70, v33
	v_cmp_lt_i32_e32 vcc, s31, v86
	s_or_b64 s[6:7], vcc, s[6:7]
	s_andn2_b64 exec, exec, s[6:7]
	s_cbranch_execz .LBB0_354
	s_branch .LBB0_352
